# a+b plus loop-invariant LDS base v_add hoisted out of the P1,P4,P5,P7 K-loops into spare VGPRs (no VALU from the loader wave inside the MFMA stream)
# speedup vs baseline: 1.0001x; 1.0001x over previous
;     __device__ bool next(int i, Unit& u) const { if (i > 1) return false; const int xcd = c & 7, idx = c >> 3; u.pm = 16 * i + 4 * (xcd >> 1) + (idx & 3); u.pn = 8 * (xcd & 1) + (idx >> 2); return true; }
; #define PG8_STAGE(bufoff, gbase, voff) do { const char* _gb = (const char*)(gbase); asm volatile("" : "+s"(_gb)); _Pragma("unroll") for (int _i = 0; _i < 2; ++_i) { asm volatile("" : "+v"((voff)[_i])); \
;         __builtin_amdgcn_global_load_lds((const unsigned*)(_gb + (voff)[_i]), (PG8_LAS unsigned*)(lds + (bufoff) + ldsw + _i * 8192), 16, 0, 0); } } while (0)
; #define PG8_LDA(dst, b, h) do { _Pragma("unroll") for (int m = 0; m < 4; ++m) _Pragma("unroll") for (int k = 0; k < 2; ++k) dst[m][k] = *(const PG8_LAS bf16x8*)(lds + PG8_SA(b, h) + aoff + m * 2048 + k * 1024); } while (0)
; #define PG8_LDB(dst, b, h) do { _Pragma("unroll") for (int n = 0; n < 2; ++n) _Pragma("unroll") for (int k = 0; k < 2; ++k) dst[n][k] = *(const PG8_LAS bf16x8*)(lds + PG8_SB(b, h) + boff + n * 2048 + k * 1024); } while (0)
; #define PG8_SCHED __builtin_amdgcn_sched_barrier(0)
; template <class Epi, class Sched, bool ALIGN_EPI = false, bool SP2 = false>
; __device__ __forceinline__ void gemm_phase(PG8_LAS unsigned char* lds, const Gemm g, const Sched& S, const Epi& E) {
;     ...
;         const bool has_next = S.next(ui + 1, nxt);
;         const char* nA = has_next ? (const char*)g.A + (size_t)nxt.pm * tstep : cA; const char* nB = has_next ? (const char*)g.Bt + (size_t)nxt.pn * tstep : cB;
;         for (int t = 0; t < nt; t += 2) {
;             const bool last = (t == nt - 2);
;             const char* a1 = cA + (size_t)(t + 1) * kstep;
;             const char* a2 = last ? nA : cA + (size_t)(t + 2) * kstep; const char* b2 = last ? nB : cB + (size_t)(t + 2) * kstep;
;             const char* a3 = a2 + kstep; const char* b3 = b2 + kstep;
;             if (last && has_next) S.a_ready(nxt);
;             if constexpr (SP2) {
;             PG8_LDB(B0, 0, 0); PG8_LDB(B1, 0, 1); PG8_SCHED; PG8_LDA(At, 0, 0); PG8_STAGE(PG8_SA(1, 1), a1 + hstep, voffA);
;     ...
; #pragma unroll
;         for (int a = 0; a < 2; ++a)
; #pragma unroll
;             for (int b = 0; b < 2; ++b)
; #pragma unroll
;                 for (int m = 0; m < 4; ++m)
; #pragma unroll
;                     for (int n = 0; n < 2; ++n) acc[a][b][m][n] = (f32x4){0.f, 0.f, 0.f, 0.f};
;         cur = nxt; cA = nA; cB = nB; ++ui;
.LBB0_312:
	s_ashr_i32 s71, s70, 31
	s_lshl_b64 s[14:15], s[70:71], 21
	s_add_u32 s74, s26, s14
	s_addc_u32 s75, s27, s15
	s_and_b64 s[14:15], s[6:7], exec
	s_cselect_b32 s11, s75, s9
	s_cselect_b32 s13, s74, s8
	s_ashr_i32 s67, s66, 31
	s_lshl_b64 s[14:15], s[66:67], 21
	s_add_u32 s84, s28, s14
	s_addc_u32 s85, s29, s15
	s_and_b64 s[14:15], s[6:7], exec
	s_cselect_b32 s33, s85, s3
	s_cselect_b32 s36, s84, s2
	s_add_u32 s37, s2, 0x100
	v_mov_b32_e32 v2, 0
	s_addc_u32 s42, s3, 0
	s_mov_b32 s43, -2
	s_waitcnt lgkmcnt(0)
	v_mov_b32_e32 v3, v2
	v_mov_b32_e32 v4, v2
	v_mov_b32_e32 v5, v2
	v_mov_b32_e32 v6, v2
	v_mov_b32_e32 v7, v2
	v_mov_b32_e32 v8, v2
	v_mov_b32_e32 v9, v2
	v_mov_b32_e32 v18, v2
	v_mov_b32_e32 v19, v2
	v_mov_b32_e32 v20, v2
	v_mov_b32_e32 v21, v2
	v_mov_b32_e32 v22, v2
	v_mov_b32_e32 v23, v2
	v_mov_b32_e32 v24, v2
	v_mov_b32_e32 v25, v2
	v_mov_b32_e32 v34, v2
	v_mov_b32_e32 v35, v2
	v_mov_b32_e32 v36, v2
	v_mov_b32_e32 v37, v2
	v_mov_b32_e32 v38, v2
	v_mov_b32_e32 v39, v2
	v_mov_b32_e32 v40, v2
	v_mov_b32_e32 v41, v2
	v_mov_b32_e32 v50, v2
	v_mov_b32_e32 v51, v2
	v_mov_b32_e32 v52, v2
	v_mov_b32_e32 v53, v2
	v_mov_b32_e32 v54, v2
	v_mov_b32_e32 v55, v2
	v_mov_b32_e32 v56, v2
	v_mov_b32_e32 v57, v2
	v_mov_b32_e32 v10, v2
	v_mov_b32_e32 v11, v2
	v_mov_b32_e32 v12, v2
	v_mov_b32_e32 v13, v2
	v_mov_b32_e32 v14, v2
	v_mov_b32_e32 v15, v2
	v_mov_b32_e32 v16, v2
	v_mov_b32_e32 v17, v2
	v_mov_b32_e32 v26, v2
	v_mov_b32_e32 v27, v2
	v_mov_b32_e32 v28, v2
	v_mov_b32_e32 v29, v2
	v_mov_b32_e32 v30, v2
	v_mov_b32_e32 v31, v2
	v_mov_b32_e32 v32, v2
	v_mov_b32_e32 v33, v2
	v_mov_b32_e32 v42, v2
	v_mov_b32_e32 v43, v2
	v_mov_b32_e32 v44, v2
	v_mov_b32_e32 v45, v2
	v_mov_b32_e32 v46, v2
	v_mov_b32_e32 v47, v2
	v_mov_b32_e32 v48, v2
	v_mov_b32_e32 v49, v2
	v_mov_b32_e32 v58, v2
	v_mov_b32_e32 v59, v2
	v_mov_b32_e32 v60, v2
	v_mov_b32_e32 v61, v2
	v_mov_b32_e32 v62, v2
	v_mov_b32_e32 v63, v2
	v_mov_b32_e32 v64, v2
	v_mov_b32_e32 v65, v2
	v_mov_b32_e32 v66, v2
	v_mov_b32_e32 v67, v2
	v_mov_b32_e32 v68, v2
	v_mov_b32_e32 v69, v2
	v_mov_b32_e32 v70, v2
	v_mov_b32_e32 v71, v2
	v_mov_b32_e32 v72, v2
	v_mov_b32_e32 v73, v2
	v_mov_b32_e32 v82, v2
	v_mov_b32_e32 v83, v2
	v_mov_b32_e32 v84, v2
	v_mov_b32_e32 v85, v2
	v_mov_b32_e32 v86, v2
	v_mov_b32_e32 v87, v2
	v_mov_b32_e32 v88, v2
	v_mov_b32_e32 v89, v2
	v_mov_b32_e32 v98, v2
	v_mov_b32_e32 v99, v2
	v_mov_b32_e32 v100, v2
	v_mov_b32_e32 v101, v2
	v_mov_b32_e32 v102, v2
	v_mov_b32_e32 v103, v2
	v_mov_b32_e32 v104, v2
	v_mov_b32_e32 v105, v2
	v_mov_b32_e32 v114, v2
	v_mov_b32_e32 v115, v2
	v_mov_b32_e32 v116, v2
	v_mov_b32_e32 v117, v2
	v_mov_b32_e32 v118, v2
	v_mov_b32_e32 v119, v2
	v_mov_b32_e32 v120, v2
	v_mov_b32_e32 v121, v2
	v_mov_b32_e32 v74, v2
	v_mov_b32_e32 v75, v2
	v_mov_b32_e32 v76, v2
	v_mov_b32_e32 v77, v2
	v_mov_b32_e32 v78, v2
	v_mov_b32_e32 v79, v2
	v_mov_b32_e32 v80, v2
	v_mov_b32_e32 v81, v2
	v_mov_b32_e32 v90, v2
	v_mov_b32_e32 v91, v2
	v_mov_b32_e32 v92, v2
	v_mov_b32_e32 v93, v2
	v_mov_b32_e32 v94, v2
	v_mov_b32_e32 v95, v2
	v_mov_b32_e32 v96, v2
	v_mov_b32_e32 v97, v2
	v_mov_b32_e32 v106, v2
	v_mov_b32_e32 v107, v2
	v_mov_b32_e32 v108, v2
	v_mov_b32_e32 v109, v2
	v_mov_b32_e32 v110, v2
	v_mov_b32_e32 v111, v2
	v_mov_b32_e32 v112, v2
	v_mov_b32_e32 v113, v2
	v_mov_b32_e32 v122, v2
	v_mov_b32_e32 v123, v2
	v_mov_b32_e32 v124, v2
	v_mov_b32_e32 v125, v2
	v_mov_b32_e32 v126, v2
	v_mov_b32_e32 v127, v2
	v_mov_b32_e32 v128, v2
	v_mov_b32_e32 v129, v2
	v_add_u32_e32 v239, 0x18000, v148
	v_add_u32_e32 v240, 0x1c000, v148
.LBB0_313:
	ds_read_b128 v[136:139], v150
	ds_read_b128 v[140:143], v150 offset:1024
	ds_read_b128 v[154:157], v150 offset:2048
	ds_read_b128 v[158:161], v150 offset:3072
	ds_read_b128 v[162:165], v151
	ds_read_b128 v[166:169], v151 offset:1024
	ds_read_b128 v[170:173], v151 offset:2048
	ds_read_b128 v[174:177], v151 offset:3072
	s_add_u32 s14, s8, 0x100
	s_addc_u32 s15, s9, 0
	s_cmp_eq_u32 s43, 60
	s_cselect_b32 s24, s13, s14
	s_cselect_b32 s25, s11, s15
	s_cselect_b32 s16, s36, s37
	s_cselect_b32 s17, s33, s42
	s_add_u32 s2, s24, 0x80
	s_addc_u32 s3, s25, 0
	s_add_u32 s8, s8, 0x100080
	s_addc_u32 s9, s9, 0
	s_add_i32 m0, s63, 0xc000
	ds_read_b128 v[178:181], v152
	ds_read_b128 v[182:185], v152 offset:1024
	ds_read_b128 v[186:189], v152 offset:2048
	ds_read_b128 v[190:193], v152 offset:3072
	ds_read_b128 v[194:197], v152 offset:4096
	ds_read_b128 v[198:201], v152 offset:5120
	ds_read_b128 v[202:205], v152 offset:6144
	ds_read_b128 v[206:209], v152 offset:7168
	s_nop 0
	global_load_lds_dwordx4 v1, s[8:9]
	s_add_i32 m0, s63, 0xe000
	s_nop 0
	global_load_lds_dwordx4 v145, s[8:9]
	s_waitcnt vmcnt(8)
	s_waitcnt lgkmcnt(0)
	s_setprio 1
	s_waitcnt lgkmcnt(0)
	s_barrier
; #define PG8_STAGE(bufoff, gbase, voff) do { const char* _gb = (const char*)(gbase); asm volatile("" : "+s"(_gb)); _Pragma("unroll") for (int _i = 0; _i < 2; ++_i) { asm volatile("" : "+v"((voff)[_i])); \
;         __builtin_amdgcn_global_load_lds((const unsigned*)(_gb + (voff)[_i]), (PG8_LAS unsigned*)(lds + (bufoff) + ldsw + _i * 8192), 16, 0, 0); } } while (0)
; #define PG8_LDA(dst, b, h) do { _Pragma("unroll") for (int m = 0; m < 4; ++m) _Pragma("unroll") for (int k = 0; k < 2; ++k) dst[m][k] = *(const PG8_LAS bf16x8*)(lds + PG8_SA(b, h) + aoff + m * 2048 + k * 1024); } while (0)
; #define PG8_LDB(dst, b, h) do { _Pragma("unroll") for (int n = 0; n < 2; ++n) _Pragma("unroll") for (int k = 0; k < 2; ++k) dst[n][k] = *(const PG8_LAS bf16x8*)(lds + PG8_SB(b, h) + boff + n * 2048 + k * 1024); } while (0)
; #define PG8_WAIT_V(n) asm volatile("s_waitcnt vmcnt(" #n ")" ::: "memory")
; #define PG8_WAIT_L(n) asm volatile("s_waitcnt lgkmcnt(" #n ")" ::: "memory")
; #define PG8_BAR __builtin_amdgcn_s_barrier()
; #define PG8_SCHED __builtin_amdgcn_sched_barrier(0)
; #define PG8_STAGE(bufoff, gbase, voff) do { const char* _gb = (const char*)(gbase); asm volatile("" : "+s"(_gb)); _Pragma("unroll") for (int _i = 0; _i < 2; ++_i) { asm volatile("" : "+v"((voff)[_i])); \
;         __builtin_amdgcn_global_load_lds((const unsigned*)(_gb + (voff)[_i]), (PG8_LAS unsigned*)(lds + (bufoff) + ldsw + _i * 8192), 16, 0, 0); } } while (0)
; #define PG8_LDA(dst, b, h) do { _Pragma("unroll") for (int m = 0; m < 4; ++m) _Pragma("unroll") for (int k = 0; k < 2; ++k) dst[m][k] = *(const PG8_LAS bf16x8*)(lds + PG8_SA(b, h) + aoff + m * 2048 + k * 1024); } while (0)
; #define PG8_WAIT_V(n) asm volatile("s_waitcnt vmcnt(" #n ")" ::: "memory")
; template <class Epi, class Sched, bool ALIGN_EPI = false, bool SP2 = false>
; __device__ __forceinline__ void gemm_phase(PG8_LAS unsigned char* lds, const Gemm g, const Sched& S, const Epi& E) {
;     ...
;             PG8_LDB(B0, 0, 0); PG8_LDB(B1, 0, 1); PG8_SCHED; PG8_LDA(At, 0, 0); PG8_STAGE(PG8_SA(1, 1), a1 + hstep, voffA);
;             PG8_WAIT_V(8); PG8_WAIT_L(0); PG8_BAR; PG8_MMA2(0); PG8_BAR; PG8_SCHED;
;             PG8_LDA(At, 0, 1); PG8_STAGE(PG8_SB(0, 0), b2, voffB); PG8_STAGE(PG8_SB(0, 1), b2 + hstep, voffB); PG8_STAGE(PG8_SA(0, 0), a2, voffA);
;             PG8_WAIT_V(8); PG8_WAIT_L(0); PG8_BAR; PG8_MMA2(1); PG8_BAR; PG8_SCHED;
	v_mfma_f32_16x16x32_bf16 v[126:129], v[136:139], v[178:181], v[126:129]
	v_mfma_f32_16x16x32_bf16 v[122:125], v[154:157], v[178:181], v[122:125]
	v_mfma_f32_16x16x32_bf16 v[110:113], v[136:139], v[186:189], v[110:113]
	v_mfma_f32_16x16x32_bf16 v[106:109], v[154:157], v[186:189], v[106:109]
	v_mfma_f32_16x16x32_bf16 v[94:97], v[136:139], v[194:197], v[94:97]
	v_mfma_f32_16x16x32_bf16 v[90:93], v[154:157], v[194:197], v[90:93]
	v_mfma_f32_16x16x32_bf16 v[78:81], v[136:139], v[202:205], v[78:81]
	v_mfma_f32_16x16x32_bf16 v[74:77], v[154:157], v[202:205], v[74:77]
	v_mfma_f32_16x16x32_bf16 v[118:121], v[162:165], v[178:181], v[118:121]
	v_mfma_f32_16x16x32_bf16 v[114:117], v[170:173], v[178:181], v[114:117]
	v_mfma_f32_16x16x32_bf16 v[102:105], v[162:165], v[186:189], v[102:105]
	v_mfma_f32_16x16x32_bf16 v[98:101], v[170:173], v[186:189], v[98:101]
	v_mfma_f32_16x16x32_bf16 v[86:89], v[162:165], v[194:197], v[86:89]
	v_mfma_f32_16x16x32_bf16 v[82:85], v[170:173], v[194:197], v[82:85]
	v_mfma_f32_16x16x32_bf16 v[70:73], v[162:165], v[202:205], v[70:73]
	v_mfma_f32_16x16x32_bf16 v[66:69], v[170:173], v[202:205], v[66:69]
	v_mfma_f32_16x16x32_bf16 v[126:129], v[140:143], v[182:185], v[126:129]
	v_mfma_f32_16x16x32_bf16 v[122:125], v[158:161], v[182:185], v[122:125]
	v_mfma_f32_16x16x32_bf16 v[110:113], v[140:143], v[190:193], v[110:113]
	v_mfma_f32_16x16x32_bf16 v[106:109], v[158:161], v[190:193], v[106:109]
	v_mfma_f32_16x16x32_bf16 v[94:97], v[140:143], v[198:201], v[94:97]
	v_mfma_f32_16x16x32_bf16 v[90:93], v[158:161], v[198:201], v[90:93]
	v_mfma_f32_16x16x32_bf16 v[78:81], v[140:143], v[206:209], v[78:81]
	v_mfma_f32_16x16x32_bf16 v[74:77], v[158:161], v[206:209], v[74:77]
	v_mfma_f32_16x16x32_bf16 v[118:121], v[166:169], v[182:185], v[118:121]
	v_mfma_f32_16x16x32_bf16 v[114:117], v[174:177], v[182:185], v[114:117]
	v_mfma_f32_16x16x32_bf16 v[102:105], v[166:169], v[190:193], v[102:105]
	v_mfma_f32_16x16x32_bf16 v[98:101], v[174:177], v[190:193], v[98:101]
	v_mfma_f32_16x16x32_bf16 v[86:89], v[166:169], v[198:201], v[86:89]
	v_mfma_f32_16x16x32_bf16 v[82:85], v[174:177], v[198:201], v[82:85]
	v_mfma_f32_16x16x32_bf16 v[70:73], v[166:169], v[206:209], v[70:73]
	v_mfma_f32_16x16x32_bf16 v[66:69], v[174:177], v[206:209], v[66:69]
	s_setprio 0
	s_barrier
	s_add_i32 s44, s95, s61
	s_mov_b64 s[8:9], s[16:17]
	s_mov_b32 m0, s44
	ds_read_b128 v[178:181], v152 offset:16384
	ds_read_b128 v[182:185], v152 offset:17408
	ds_read_b128 v[186:189], v152 offset:18432
	ds_read_b128 v[190:193], v152 offset:19456
	ds_read_b128 v[194:197], v152 offset:20480
	ds_read_b128 v[198:201], v152 offset:21504
	ds_read_b128 v[202:205], v152 offset:22528
	ds_read_b128 v[206:209], v152 offset:23552
	s_nop 0
	global_load_lds_dwordx4 v144, s[8:9]
	s_add_i32 m0, s44, 0x2000
	s_nop 0
	global_load_lds_dwordx4 v146, s[8:9]
	s_add_u32 s8, s16, 0x100000
	s_addc_u32 s9, s17, 0
	s_add_i32 s44, s96, s61
	s_mov_b32 m0, s44
	s_nop 0
	global_load_lds_dwordx4 v144, s[8:9]
	s_add_i32 m0, s44, 0x2000
	s_nop 0
	global_load_lds_dwordx4 v146, s[8:9]
	s_mov_b64 s[8:9], s[24:25]
	s_mov_b32 m0, s63
	s_nop 0
	global_load_lds_dwordx4 v1, s[8:9]
	s_mov_b32 m0, s65
	s_nop 0
	global_load_lds_dwordx4 v145, s[8:9]
	s_waitcnt vmcnt(8)
	s_waitcnt lgkmcnt(0)
	s_setprio 1
	s_waitcnt lgkmcnt(0)
	s_barrier
	v_mfma_f32_16x16x32_bf16 v[62:65], v[136:139], v[178:181], v[62:65]
	v_mfma_f32_16x16x32_bf16 v[58:61], v[154:157], v[178:181], v[58:61]
	v_mfma_f32_16x16x32_bf16 v[46:49], v[136:139], v[186:189], v[46:49]
	v_mfma_f32_16x16x32_bf16 v[42:45], v[154:157], v[186:189], v[42:45]
	v_mfma_f32_16x16x32_bf16 v[30:33], v[136:139], v[194:197], v[30:33]
	v_mfma_f32_16x16x32_bf16 v[26:29], v[154:157], v[194:197], v[26:29]
	v_mfma_f32_16x16x32_bf16 v[14:17], v[136:139], v[202:205], v[14:17]
	v_mfma_f32_16x16x32_bf16 v[10:13], v[154:157], v[202:205], v[10:13]
	v_mfma_f32_16x16x32_bf16 v[54:57], v[162:165], v[178:181], v[54:57]
	v_mfma_f32_16x16x32_bf16 v[50:53], v[170:173], v[178:181], v[50:53]
	v_mfma_f32_16x16x32_bf16 v[38:41], v[162:165], v[186:189], v[38:41]
	v_mfma_f32_16x16x32_bf16 v[34:37], v[170:173], v[186:189], v[34:37]
	v_mfma_f32_16x16x32_bf16 v[22:25], v[162:165], v[194:197], v[22:25]
	v_mfma_f32_16x16x32_bf16 v[18:21], v[170:173], v[194:197], v[18:21]
	v_mfma_f32_16x16x32_bf16 v[6:9], v[162:165], v[202:205], v[6:9]
	v_mfma_f32_16x16x32_bf16 v[2:5], v[170:173], v[202:205], v[2:5]
	v_mfma_f32_16x16x32_bf16 v[62:65], v[140:143], v[182:185], v[62:65]
	v_mfma_f32_16x16x32_bf16 v[58:61], v[158:161], v[182:185], v[58:61]
	v_mfma_f32_16x16x32_bf16 v[46:49], v[140:143], v[190:193], v[46:49]
	v_mfma_f32_16x16x32_bf16 v[42:45], v[158:161], v[190:193], v[42:45]
	v_mfma_f32_16x16x32_bf16 v[30:33], v[140:143], v[198:201], v[30:33]
	v_mfma_f32_16x16x32_bf16 v[26:29], v[158:161], v[198:201], v[26:29]
	v_mfma_f32_16x16x32_bf16 v[14:17], v[140:143], v[206:209], v[14:17]
	v_mfma_f32_16x16x32_bf16 v[10:13], v[158:161], v[206:209], v[10:13]
	v_mfma_f32_16x16x32_bf16 v[54:57], v[166:169], v[182:185], v[54:57]
	v_mfma_f32_16x16x32_bf16 v[50:53], v[174:177], v[182:185], v[50:53]
	v_mfma_f32_16x16x32_bf16 v[38:41], v[166:169], v[190:193], v[38:41]
	v_mfma_f32_16x16x32_bf16 v[34:37], v[174:177], v[190:193], v[34:37]
	v_mfma_f32_16x16x32_bf16 v[22:25], v[166:169], v[198:201], v[22:25]
	v_mfma_f32_16x16x32_bf16 v[18:21], v[174:177], v[198:201], v[18:21]
	v_mfma_f32_16x16x32_bf16 v[6:9], v[166:169], v[206:209], v[6:9]
	v_mfma_f32_16x16x32_bf16 v[2:5], v[174:177], v[206:209], v[2:5]
	s_setprio 0
	s_barrier
; #define PG8_STAGE(bufoff, gbase, voff) do { const char* _gb = (const char*)(gbase); asm volatile("" : "+s"(_gb)); _Pragma("unroll") for (int _i = 0; _i < 2; ++_i) { asm volatile("" : "+v"((voff)[_i])); \
;         __builtin_amdgcn_global_load_lds((const unsigned*)(_gb + (voff)[_i]), (PG8_LAS unsigned*)(lds + (bufoff) + ldsw + _i * 8192), 16, 0, 0); } } while (0)
; #define PG8_LDA(dst, b, h) do { _Pragma("unroll") for (int m = 0; m < 4; ++m) _Pragma("unroll") for (int k = 0; k < 2; ++k) dst[m][k] = *(const PG8_LAS bf16x8*)(lds + PG8_SA(b, h) + aoff + m * 2048 + k * 1024); } while (0)
; #define PG8_LDB(dst, b, h) do { _Pragma("unroll") for (int n = 0; n < 2; ++n) _Pragma("unroll") for (int k = 0; k < 2; ++k) dst[n][k] = *(const PG8_LAS bf16x8*)(lds + PG8_SB(b, h) + boff + n * 2048 + k * 1024); } while (0)
; #define PG8_WAIT_V(n) asm volatile("s_waitcnt vmcnt(" #n ")" ::: "memory")
; #define PG8_WAIT_L(n) asm volatile("s_waitcnt lgkmcnt(" #n ")" ::: "memory")
; #define PG8_BAR __builtin_amdgcn_s_barrier()
; #define PG8_SCHED __builtin_amdgcn_sched_barrier(0)
; #define PG8_STAGE(bufoff, gbase, voff) do { const char* _gb = (const char*)(gbase); asm volatile("" : "+s"(_gb)); _Pragma("unroll") for (int _i = 0; _i < 2; ++_i) { asm volatile("" : "+v"((voff)[_i])); \
;         __builtin_amdgcn_global_load_lds((const unsigned*)(_gb + (voff)[_i]), (PG8_LAS unsigned*)(lds + (bufoff) + ldsw + _i * 8192), 16, 0, 0); } } while (0)
; #define PG8_LDA(dst, b, h) do { _Pragma("unroll") for (int m = 0; m < 4; ++m) _Pragma("unroll") for (int k = 0; k < 2; ++k) dst[m][k] = *(const PG8_LAS bf16x8*)(lds + PG8_SA(b, h) + aoff + m * 2048 + k * 1024); } while (0)
; #define PG8_WAIT_V(n) asm volatile("s_waitcnt vmcnt(" #n ")" ::: "memory")
; template <class Epi, class Sched, bool ALIGN_EPI = false, bool SP2 = false>
; __device__ __forceinline__ void gemm_phase(PG8_LAS unsigned char* lds, const Gemm g, const Sched& S, const Epi& E) {
;     ...
;             PG8_LDB(B0, 1, 0); PG8_LDB(B1, 1, 1); PG8_SCHED; PG8_LDA(At, 1, 0); PG8_STAGE(PG8_SA(0, 1), a2 + hstep, voffA);
;             PG8_WAIT_V(8); PG8_WAIT_L(0); PG8_BAR; PG8_MMA2(0); PG8_BAR; PG8_SCHED;
;             PG8_LDA(At, 1, 1); PG8_STAGE(PG8_SB(1, 0), b3, voffB); PG8_STAGE(PG8_SB(1, 1), b3 + hstep, voffB); PG8_STAGE(PG8_SA(1, 0), a3, voffA);
;             PG8_WAIT_V(8); PG8_WAIT_L(0); PG8_BAR; PG8_MMA2(1); PG8_BAR; PG8_SCHED;
	s_add_i32 s44, 0, 0x18000
	s_add_i32 s45, 0, 0x1c000
	ds_read_b128 v[136:139], v239
	ds_read_b128 v[140:143], v239 offset:1024
	ds_read_b128 v[154:157], v239 offset:2048
	ds_read_b128 v[158:161], v239 offset:3072
	ds_read_b128 v[162:165], v240
	ds_read_b128 v[166:169], v240 offset:1024
	ds_read_b128 v[170:173], v240 offset:2048
	ds_read_b128 v[174:177], v240 offset:3072
	s_add_u32 s8, s24, 0x100000
	s_addc_u32 s9, s25, 0
	s_mov_b32 m0, s88
	ds_read_b128 v[178:181], v152 offset:32768
	ds_read_b128 v[182:185], v152 offset:33792
	ds_read_b128 v[186:189], v152 offset:34816
	ds_read_b128 v[190:193], v152 offset:35840
	ds_read_b128 v[194:197], v152 offset:36864
	ds_read_b128 v[198:201], v152 offset:37888
	ds_read_b128 v[202:205], v152 offset:38912
	ds_read_b128 v[206:209], v152 offset:39936
	s_nop 0
	global_load_lds_dwordx4 v1, s[8:9]
	s_mov_b32 m0, s89
	s_nop 0
	global_load_lds_dwordx4 v145, s[8:9]
	s_waitcnt vmcnt(8)
	s_waitcnt lgkmcnt(0)
	s_setprio 1
	s_waitcnt lgkmcnt(0)
	s_barrier
	v_mfma_f32_16x16x32_bf16 v[126:129], v[136:139], v[178:181], v[126:129]
	v_mfma_f32_16x16x32_bf16 v[122:125], v[154:157], v[178:181], v[122:125]
	v_mfma_f32_16x16x32_bf16 v[110:113], v[136:139], v[186:189], v[110:113]
	v_mfma_f32_16x16x32_bf16 v[106:109], v[154:157], v[186:189], v[106:109]
	v_mfma_f32_16x16x32_bf16 v[94:97], v[136:139], v[194:197], v[94:97]
	v_mfma_f32_16x16x32_bf16 v[90:93], v[154:157], v[194:197], v[90:93]
	v_mfma_f32_16x16x32_bf16 v[78:81], v[136:139], v[202:205], v[78:81]
	v_mfma_f32_16x16x32_bf16 v[74:77], v[154:157], v[202:205], v[74:77]
	v_mfma_f32_16x16x32_bf16 v[118:121], v[162:165], v[178:181], v[118:121]
	v_mfma_f32_16x16x32_bf16 v[114:117], v[170:173], v[178:181], v[114:117]
	v_mfma_f32_16x16x32_bf16 v[102:105], v[162:165], v[186:189], v[102:105]
	v_mfma_f32_16x16x32_bf16 v[98:101], v[170:173], v[186:189], v[98:101]
	v_mfma_f32_16x16x32_bf16 v[86:89], v[162:165], v[194:197], v[86:89]
	v_mfma_f32_16x16x32_bf16 v[82:85], v[170:173], v[194:197], v[82:85]
	v_mfma_f32_16x16x32_bf16 v[70:73], v[162:165], v[202:205], v[70:73]
	v_mfma_f32_16x16x32_bf16 v[66:69], v[170:173], v[202:205], v[66:69]
	v_mfma_f32_16x16x32_bf16 v[126:129], v[140:143], v[182:185], v[126:129]
	v_mfma_f32_16x16x32_bf16 v[122:125], v[158:161], v[182:185], v[122:125]
	v_mfma_f32_16x16x32_bf16 v[110:113], v[140:143], v[190:193], v[110:113]
	v_mfma_f32_16x16x32_bf16 v[106:109], v[158:161], v[190:193], v[106:109]
	v_mfma_f32_16x16x32_bf16 v[94:97], v[140:143], v[198:201], v[94:97]
	v_mfma_f32_16x16x32_bf16 v[90:93], v[158:161], v[198:201], v[90:93]
	v_mfma_f32_16x16x32_bf16 v[78:81], v[140:143], v[206:209], v[78:81]
	v_mfma_f32_16x16x32_bf16 v[74:77], v[158:161], v[206:209], v[74:77]
	v_mfma_f32_16x16x32_bf16 v[118:121], v[166:169], v[182:185], v[118:121]
	v_mfma_f32_16x16x32_bf16 v[114:117], v[174:177], v[182:185], v[114:117]
	v_mfma_f32_16x16x32_bf16 v[102:105], v[166:169], v[190:193], v[102:105]
	v_mfma_f32_16x16x32_bf16 v[98:101], v[174:177], v[190:193], v[98:101]
	v_mfma_f32_16x16x32_bf16 v[86:89], v[166:169], v[198:201], v[86:89]
	v_mfma_f32_16x16x32_bf16 v[82:85], v[174:177], v[198:201], v[82:85]
	v_mfma_f32_16x16x32_bf16 v[70:73], v[166:169], v[206:209], v[70:73]
	v_mfma_f32_16x16x32_bf16 v[66:69], v[174:177], v[206:209], v[66:69]
	s_setprio 0
	s_barrier
	s_add_u32 s8, s16, 0x80
	s_addc_u32 s9, s17, 0
	s_add_i32 s24, s44, s61
	s_mov_b32 m0, s24
	ds_read_b128 v[178:181], v152 offset:49152
	ds_read_b128 v[182:185], v152 offset:50176
	ds_read_b128 v[186:189], v152 offset:51200
	ds_read_b128 v[190:193], v152 offset:52224
	ds_read_b128 v[194:197], v152 offset:53248
	ds_read_b128 v[198:201], v152 offset:54272
	ds_read_b128 v[202:205], v152 offset:55296
	ds_read_b128 v[206:209], v152 offset:56320
	s_nop 0
	global_load_lds_dwordx4 v144, s[8:9]
	s_add_i32 m0, s24, 0x2000
	s_nop 0
	global_load_lds_dwordx4 v146, s[8:9]
	s_add_u32 s8, s16, 0x100080
	s_addc_u32 s9, s17, 0
	s_add_i32 s16, s45, s61
	s_mov_b32 m0, s16
	s_nop 0
	global_load_lds_dwordx4 v144, s[8:9]
	s_add_i32 m0, s16, 0x2000
	s_nop 0
	global_load_lds_dwordx4 v146, s[8:9]
	s_mov_b32 m0, s91
	s_nop 0
	global_load_lds_dwordx4 v1, s[2:3]
	s_mov_b32 m0, s92
	s_nop 0
	global_load_lds_dwordx4 v145, s[2:3]
	s_waitcnt vmcnt(8)
	s_waitcnt lgkmcnt(0)
	s_setprio 1
	s_waitcnt lgkmcnt(0)
	s_barrier
	v_mfma_f32_16x16x32_bf16 v[62:65], v[136:139], v[178:181], v[62:65]
	v_mfma_f32_16x16x32_bf16 v[58:61], v[154:157], v[178:181], v[58:61]
	v_mfma_f32_16x16x32_bf16 v[46:49], v[136:139], v[186:189], v[46:49]
	v_mfma_f32_16x16x32_bf16 v[42:45], v[154:157], v[186:189], v[42:45]
	v_mfma_f32_16x16x32_bf16 v[30:33], v[136:139], v[194:197], v[30:33]
	v_mfma_f32_16x16x32_bf16 v[26:29], v[154:157], v[194:197], v[26:29]
	v_mfma_f32_16x16x32_bf16 v[14:17], v[136:139], v[202:205], v[14:17]
	v_mfma_f32_16x16x32_bf16 v[10:13], v[154:157], v[202:205], v[10:13]
	v_mfma_f32_16x16x32_bf16 v[54:57], v[162:165], v[178:181], v[54:57]
	v_mfma_f32_16x16x32_bf16 v[50:53], v[170:173], v[178:181], v[50:53]
	v_mfma_f32_16x16x32_bf16 v[38:41], v[162:165], v[186:189], v[38:41]
	v_mfma_f32_16x16x32_bf16 v[34:37], v[170:173], v[186:189], v[34:37]
	v_mfma_f32_16x16x32_bf16 v[22:25], v[162:165], v[194:197], v[22:25]
	v_mfma_f32_16x16x32_bf16 v[18:21], v[170:173], v[194:197], v[18:21]
	v_mfma_f32_16x16x32_bf16 v[6:9], v[162:165], v[202:205], v[6:9]
	v_mfma_f32_16x16x32_bf16 v[2:5], v[170:173], v[202:205], v[2:5]
	v_mfma_f32_16x16x32_bf16 v[62:65], v[140:143], v[182:185], v[62:65]
	v_mfma_f32_16x16x32_bf16 v[58:61], v[158:161], v[182:185], v[58:61]
	v_mfma_f32_16x16x32_bf16 v[46:49], v[140:143], v[190:193], v[46:49]
	v_mfma_f32_16x16x32_bf16 v[42:45], v[158:161], v[190:193], v[42:45]
	v_mfma_f32_16x16x32_bf16 v[30:33], v[140:143], v[198:201], v[30:33]
	v_mfma_f32_16x16x32_bf16 v[26:29], v[158:161], v[198:201], v[26:29]
	v_mfma_f32_16x16x32_bf16 v[14:17], v[140:143], v[206:209], v[14:17]
	v_mfma_f32_16x16x32_bf16 v[10:13], v[158:161], v[206:209], v[10:13]
	v_mfma_f32_16x16x32_bf16 v[54:57], v[166:169], v[182:185], v[54:57]
	v_mfma_f32_16x16x32_bf16 v[50:53], v[174:177], v[182:185], v[50:53]
	v_mfma_f32_16x16x32_bf16 v[38:41], v[166:169], v[190:193], v[38:41]
	v_mfma_f32_16x16x32_bf16 v[34:37], v[174:177], v[190:193], v[34:37]
	v_mfma_f32_16x16x32_bf16 v[22:25], v[166:169], v[198:201], v[22:25]
	v_mfma_f32_16x16x32_bf16 v[18:21], v[174:177], v[198:201], v[18:21]
	v_mfma_f32_16x16x32_bf16 v[6:9], v[166:169], v[206:209], v[6:9]
	v_mfma_f32_16x16x32_bf16 v[2:5], v[174:177], v[206:209], v[2:5]
	s_setprio 0
	s_barrier
	s_add_i32 s43, s43, 2
	s_add_u32 s37, s37, 0x100
	s_addc_u32 s42, s42, 0
	s_cmp_gt_u32 s43, 61
	s_mov_b64 s[8:9], s[14:15]
	s_cbranch_scc0 .LBB0_313
	s_and_b64 vcc, exec, s[58:59]
	s_cbranch_vccz .LBB0_333
	s_barrier
	s_cmp_lt_i32 s12, 24
	s_cbranch_scc0 .LBB0_334

;     __device__ bool next(int i, Unit& u) const { if (i > 1) return false; const int xcd = c & 7, idx = c >> 3; u.pm = 16 * i + 4 * (xcd >> 1) + (idx & 3); u.pn = 8 * (xcd & 1) + (idx >> 2); return true; }
; #define PG8_STAGE(bufoff, gbase, voff) do { const char* _gb = (const char*)(gbase); asm volatile("" : "+s"(_gb)); _Pragma("unroll") for (int _i = 0; _i < 2; ++_i) { asm volatile("" : "+v"((voff)[_i])); \
;         __builtin_amdgcn_global_load_lds((const unsigned*)(_gb + (voff)[_i]), (PG8_LAS unsigned*)(lds + (bufoff) + ldsw + _i * 8192), 16, 0, 0); } } while (0)
; #define PG8_LDA(dst, b, h) do { _Pragma("unroll") for (int m = 0; m < 4; ++m) _Pragma("unroll") for (int k = 0; k < 2; ++k) dst[m][k] = *(const PG8_LAS bf16x8*)(lds + PG8_SA(b, h) + aoff + m * 2048 + k * 1024); } while (0)
; #define PG8_LDB(dst, b, h) do { _Pragma("unroll") for (int n = 0; n < 2; ++n) _Pragma("unroll") for (int k = 0; k < 2; ++k) dst[n][k] = *(const PG8_LAS bf16x8*)(lds + PG8_SB(b, h) + boff + n * 2048 + k * 1024); } while (0)
; #define PG8_SCHED __builtin_amdgcn_sched_barrier(0)
; template <class Epi, class Sched, bool ALIGN_EPI = false, bool SP2 = false>
; __device__ __forceinline__ void gemm_phase(PG8_LAS unsigned char* lds, const Gemm g, const Sched& S, const Epi& E) {
;     ...
;         const bool has_next = S.next(ui + 1, nxt);
;         const char* nA = has_next ? (const char*)g.A + (size_t)nxt.pm * tstep : cA; const char* nB = has_next ? (const char*)g.Bt + (size_t)nxt.pn * tstep : cB;
;         for (int t = 0; t < nt; t += 2) {
;             const bool last = (t == nt - 2);
;             const char* a1 = cA + (size_t)(t + 1) * kstep;
;             const char* a2 = last ? nA : cA + (size_t)(t + 2) * kstep; const char* b2 = last ? nB : cB + (size_t)(t + 2) * kstep;
;             const char* a3 = a2 + kstep; const char* b3 = b2 + kstep;
;             if (last && has_next) S.a_ready(nxt);
;             if constexpr (SP2) {
;             PG8_LDB(B0, 0, 0); PG8_LDB(B1, 0, 1); PG8_SCHED; PG8_LDA(At, 0, 0); PG8_STAGE(PG8_SA(1, 1), a1 + hstep, voffA);
;     ...
; #pragma unroll
;         for (int a = 0; a < 2; ++a)
; #pragma unroll
;             for (int b = 0; b < 2; ++b)
; #pragma unroll
;                 for (int m = 0; m < 4; ++m)
; #pragma unroll
;                     for (int n = 0; n < 2; ++n) acc[a][b][m][n] = (f32x4){0.f, 0.f, 0.f, 0.f};
;         cur = nxt; cA = nA; cB = nB; ++ui;
.LBB0_832:
	s_ashr_i32 s55, s54, 31
	s_lshl_b64 s[24:25], s[54:55], 21
	s_add_u32 s56, s33, s24
	s_addc_u32 s57, s96, s25
	s_and_b64 s[24:25], s[4:5], exec
	s_cselect_b32 s55, s57, s17
	s_cselect_b32 s83, s56, s16
	s_ashr_i32 s53, s52, 31
	s_lshl_b64 s[24:25], s[52:53], 21
	s_add_u32 s62, s97, s24
	s_addc_u32 s63, s72, s25
	s_and_b64 s[24:25], s[4:5], exec
	s_cselect_b32 s53, s63, s3
	s_cselect_b32 s84, s62, s2
	s_add_u32 s85, s2, 0x100
	v_mov_b32_e32 v2, 0
	s_addc_u32 s86, s3, 0
	s_mov_b32 s87, -2
	s_waitcnt lgkmcnt(0)
	v_mov_b32_e32 v3, v2
	v_mov_b32_e32 v4, v2
	v_mov_b32_e32 v5, v2
	v_mov_b32_e32 v6, v2
	v_mov_b32_e32 v7, v2
	v_mov_b32_e32 v8, v2
	v_mov_b32_e32 v9, v2
	v_mov_b32_e32 v18, v2
	v_mov_b32_e32 v19, v2
	v_mov_b32_e32 v20, v2
	v_mov_b32_e32 v21, v2
	v_mov_b32_e32 v22, v2
	v_mov_b32_e32 v23, v2
	v_mov_b32_e32 v24, v2
	v_mov_b32_e32 v25, v2
	v_mov_b32_e32 v34, v2
	v_mov_b32_e32 v35, v2
	v_mov_b32_e32 v36, v2
	v_mov_b32_e32 v37, v2
	v_mov_b32_e32 v38, v2
	v_mov_b32_e32 v39, v2
	v_mov_b32_e32 v40, v2
	v_mov_b32_e32 v41, v2
	v_mov_b32_e32 v50, v2
	v_mov_b32_e32 v51, v2
	v_mov_b32_e32 v52, v2
	v_mov_b32_e32 v53, v2
	v_mov_b32_e32 v54, v2
	v_mov_b32_e32 v55, v2
	v_mov_b32_e32 v56, v2
	v_mov_b32_e32 v57, v2
	v_mov_b32_e32 v10, v2
	v_mov_b32_e32 v11, v2
	v_mov_b32_e32 v12, v2
	v_mov_b32_e32 v13, v2
	v_mov_b32_e32 v14, v2
	v_mov_b32_e32 v15, v2
	v_mov_b32_e32 v16, v2
	v_mov_b32_e32 v17, v2
	v_mov_b32_e32 v26, v2
	v_mov_b32_e32 v27, v2
	v_mov_b32_e32 v28, v2
	v_mov_b32_e32 v29, v2
	v_mov_b32_e32 v30, v2
	v_mov_b32_e32 v31, v2
	v_mov_b32_e32 v32, v2
	v_mov_b32_e32 v33, v2
	v_mov_b32_e32 v42, v2
	v_mov_b32_e32 v43, v2
	v_mov_b32_e32 v44, v2
	v_mov_b32_e32 v45, v2
	v_mov_b32_e32 v46, v2
	v_mov_b32_e32 v47, v2
	v_mov_b32_e32 v48, v2
	v_mov_b32_e32 v49, v2
	v_mov_b32_e32 v58, v2
	v_mov_b32_e32 v59, v2
	v_mov_b32_e32 v60, v2
	v_mov_b32_e32 v61, v2
	v_mov_b32_e32 v62, v2
	v_mov_b32_e32 v63, v2
	v_mov_b32_e32 v64, v2
	v_mov_b32_e32 v65, v2
	v_mov_b32_e32 v66, v2
	v_mov_b32_e32 v67, v2
	v_mov_b32_e32 v68, v2
	v_mov_b32_e32 v69, v2
	v_mov_b32_e32 v70, v2
	v_mov_b32_e32 v71, v2
	v_mov_b32_e32 v72, v2
	v_mov_b32_e32 v73, v2
	v_mov_b32_e32 v82, v2
	v_mov_b32_e32 v83, v2
	v_mov_b32_e32 v84, v2
	v_mov_b32_e32 v85, v2
	v_mov_b32_e32 v86, v2
	v_mov_b32_e32 v87, v2
	v_mov_b32_e32 v88, v2
	v_mov_b32_e32 v89, v2
	v_mov_b32_e32 v98, v2
	v_mov_b32_e32 v99, v2
	v_mov_b32_e32 v100, v2
	v_mov_b32_e32 v101, v2
	v_mov_b32_e32 v102, v2
	v_mov_b32_e32 v103, v2
	v_mov_b32_e32 v104, v2
	v_mov_b32_e32 v105, v2
	v_mov_b32_e32 v114, v2
	v_mov_b32_e32 v115, v2
	v_mov_b32_e32 v116, v2
	v_mov_b32_e32 v117, v2
	v_mov_b32_e32 v118, v2
	v_mov_b32_e32 v119, v2
	v_mov_b32_e32 v120, v2
	v_mov_b32_e32 v121, v2
	v_mov_b32_e32 v74, v2
	v_mov_b32_e32 v75, v2
	v_mov_b32_e32 v76, v2
	v_mov_b32_e32 v77, v2
	v_mov_b32_e32 v78, v2
	v_mov_b32_e32 v79, v2
	v_mov_b32_e32 v80, v2
	v_mov_b32_e32 v81, v2
	v_mov_b32_e32 v90, v2
	v_mov_b32_e32 v91, v2
	v_mov_b32_e32 v92, v2
	v_mov_b32_e32 v93, v2
	v_mov_b32_e32 v94, v2
	v_mov_b32_e32 v95, v2
	v_mov_b32_e32 v96, v2
	v_mov_b32_e32 v97, v2
	v_mov_b32_e32 v106, v2
	v_mov_b32_e32 v107, v2
	v_mov_b32_e32 v108, v2
	v_mov_b32_e32 v109, v2
	v_mov_b32_e32 v110, v2
	v_mov_b32_e32 v111, v2
	v_mov_b32_e32 v112, v2
	v_mov_b32_e32 v113, v2
	v_mov_b32_e32 v122, v2
	v_mov_b32_e32 v123, v2
	v_mov_b32_e32 v124, v2
	v_mov_b32_e32 v125, v2
	v_mov_b32_e32 v126, v2
	v_mov_b32_e32 v127, v2
	v_mov_b32_e32 v128, v2
	v_mov_b32_e32 v129, v2
	v_add_u32_e32 v239, 0x18000, v178
	v_add_u32_e32 v240, 0x1c000, v178
.LBB0_833:
	ds_read_b128 v[130:133], v180
	ds_read_b128 v[134:137], v180 offset:1024
	ds_read_b128 v[138:141], v180 offset:2048
	ds_read_b128 v[142:145], v180 offset:3072
	ds_read_b128 v[146:149], v181
	ds_read_b128 v[150:153], v181 offset:1024
	ds_read_b128 v[154:157], v181 offset:2048
	ds_read_b128 v[158:161], v181 offset:3072
	s_add_u32 s24, s16, 0x100
	s_addc_u32 s25, s17, 0
	s_cmp_eq_u32 s87, 60
	s_cselect_b32 s28, s83, s24
	s_cselect_b32 s29, s55, s25
	s_cselect_b32 s26, s84, s85
	s_cselect_b32 s27, s53, s86
	s_add_u32 s2, s28, 0x80
	s_addc_u32 s3, s29, 0
	s_add_u32 s16, s16, 0x100080
	s_addc_u32 s17, s17, 0
	s_add_i32 m0, s69, 0xc000
	ds_read_b128 v[166:169], v182
	ds_read_b128 v[170:173], v182 offset:1024
	ds_read_b128 v[184:187], v182 offset:2048
	ds_read_b128 v[188:191], v182 offset:3072
	ds_read_b128 v[192:195], v182 offset:4096
	ds_read_b128 v[196:199], v182 offset:5120
	ds_read_b128 v[200:203], v182 offset:6144
	ds_read_b128 v[204:207], v182 offset:7168
	s_nop 0
	global_load_lds_dwordx4 v1, s[16:17]
	s_add_i32 m0, s69, 0xe000
	s_nop 0
	global_load_lds_dwordx4 v175, s[16:17]
	s_waitcnt vmcnt(8)
	s_waitcnt lgkmcnt(0)
	s_setprio 1
	s_waitcnt lgkmcnt(0)
	s_barrier
; #define PG8_STAGE(bufoff, gbase, voff) do { const char* _gb = (const char*)(gbase); asm volatile("" : "+s"(_gb)); _Pragma("unroll") for (int _i = 0; _i < 2; ++_i) { asm volatile("" : "+v"((voff)[_i])); \
;         __builtin_amdgcn_global_load_lds((const unsigned*)(_gb + (voff)[_i]), (PG8_LAS unsigned*)(lds + (bufoff) + ldsw + _i * 8192), 16, 0, 0); } } while (0)
; #define PG8_LDA(dst, b, h) do { _Pragma("unroll") for (int m = 0; m < 4; ++m) _Pragma("unroll") for (int k = 0; k < 2; ++k) dst[m][k] = *(const PG8_LAS bf16x8*)(lds + PG8_SA(b, h) + aoff + m * 2048 + k * 1024); } while (0)
; #define PG8_LDB(dst, b, h) do { _Pragma("unroll") for (int n = 0; n < 2; ++n) _Pragma("unroll") for (int k = 0; k < 2; ++k) dst[n][k] = *(const PG8_LAS bf16x8*)(lds + PG8_SB(b, h) + boff + n * 2048 + k * 1024); } while (0)
; #define PG8_WAIT_V(n) asm volatile("s_waitcnt vmcnt(" #n ")" ::: "memory")
; #define PG8_WAIT_L(n) asm volatile("s_waitcnt lgkmcnt(" #n ")" ::: "memory")
; #define PG8_BAR __builtin_amdgcn_s_barrier()
; #define PG8_SCHED __builtin_amdgcn_sched_barrier(0)
; #define PG8_STAGE(bufoff, gbase, voff) do { const char* _gb = (const char*)(gbase); asm volatile("" : "+s"(_gb)); _Pragma("unroll") for (int _i = 0; _i < 2; ++_i) { asm volatile("" : "+v"((voff)[_i])); \
;         __builtin_amdgcn_global_load_lds((const unsigned*)(_gb + (voff)[_i]), (PG8_LAS unsigned*)(lds + (bufoff) + ldsw + _i * 8192), 16, 0, 0); } } while (0)
; #define PG8_LDA(dst, b, h) do { _Pragma("unroll") for (int m = 0; m < 4; ++m) _Pragma("unroll") for (int k = 0; k < 2; ++k) dst[m][k] = *(const PG8_LAS bf16x8*)(lds + PG8_SA(b, h) + aoff + m * 2048 + k * 1024); } while (0)
; #define PG8_WAIT_V(n) asm volatile("s_waitcnt vmcnt(" #n ")" ::: "memory")
; template <class Epi, class Sched, bool ALIGN_EPI = false, bool SP2 = false>
; __device__ __forceinline__ void gemm_phase(PG8_LAS unsigned char* lds, const Gemm g, const Sched& S, const Epi& E) {
;     ...
;             PG8_LDB(B0, 0, 0); PG8_LDB(B1, 0, 1); PG8_SCHED; PG8_LDA(At, 0, 0); PG8_STAGE(PG8_SA(1, 1), a1 + hstep, voffA);
;             PG8_WAIT_V(8); PG8_WAIT_L(0); PG8_BAR; PG8_MMA2(0); PG8_BAR; PG8_SCHED;
;             PG8_LDA(At, 0, 1); PG8_STAGE(PG8_SB(0, 0), b2, voffB); PG8_STAGE(PG8_SB(0, 1), b2 + hstep, voffB); PG8_STAGE(PG8_SA(0, 0), a2, voffA);
;             PG8_WAIT_V(8); PG8_WAIT_L(0); PG8_BAR; PG8_MMA2(1); PG8_BAR; PG8_SCHED;
	v_mfma_f32_16x16x32_bf16 v[126:129], v[130:133], v[166:169], v[126:129]
	v_mfma_f32_16x16x32_bf16 v[122:125], v[138:141], v[166:169], v[122:125]
	v_mfma_f32_16x16x32_bf16 v[110:113], v[130:133], v[184:187], v[110:113]
	v_mfma_f32_16x16x32_bf16 v[106:109], v[138:141], v[184:187], v[106:109]
	v_mfma_f32_16x16x32_bf16 v[94:97], v[130:133], v[192:195], v[94:97]
	v_mfma_f32_16x16x32_bf16 v[90:93], v[138:141], v[192:195], v[90:93]
	v_mfma_f32_16x16x32_bf16 v[78:81], v[130:133], v[200:203], v[78:81]
	v_mfma_f32_16x16x32_bf16 v[74:77], v[138:141], v[200:203], v[74:77]
	v_mfma_f32_16x16x32_bf16 v[118:121], v[146:149], v[166:169], v[118:121]
	v_mfma_f32_16x16x32_bf16 v[114:117], v[154:157], v[166:169], v[114:117]
	v_mfma_f32_16x16x32_bf16 v[102:105], v[146:149], v[184:187], v[102:105]
	v_mfma_f32_16x16x32_bf16 v[98:101], v[154:157], v[184:187], v[98:101]
	v_mfma_f32_16x16x32_bf16 v[86:89], v[146:149], v[192:195], v[86:89]
	v_mfma_f32_16x16x32_bf16 v[82:85], v[154:157], v[192:195], v[82:85]
	v_mfma_f32_16x16x32_bf16 v[70:73], v[146:149], v[200:203], v[70:73]
	v_mfma_f32_16x16x32_bf16 v[66:69], v[154:157], v[200:203], v[66:69]
	v_mfma_f32_16x16x32_bf16 v[126:129], v[134:137], v[170:173], v[126:129]
	v_mfma_f32_16x16x32_bf16 v[122:125], v[142:145], v[170:173], v[122:125]
	v_mfma_f32_16x16x32_bf16 v[110:113], v[134:137], v[188:191], v[110:113]
	v_mfma_f32_16x16x32_bf16 v[106:109], v[142:145], v[188:191], v[106:109]
	v_mfma_f32_16x16x32_bf16 v[94:97], v[134:137], v[196:199], v[94:97]
	v_mfma_f32_16x16x32_bf16 v[90:93], v[142:145], v[196:199], v[90:93]
	v_mfma_f32_16x16x32_bf16 v[78:81], v[134:137], v[204:207], v[78:81]
	v_mfma_f32_16x16x32_bf16 v[74:77], v[142:145], v[204:207], v[74:77]
	v_mfma_f32_16x16x32_bf16 v[118:121], v[150:153], v[170:173], v[118:121]
	v_mfma_f32_16x16x32_bf16 v[114:117], v[158:161], v[170:173], v[114:117]
	v_mfma_f32_16x16x32_bf16 v[102:105], v[150:153], v[188:191], v[102:105]
	v_mfma_f32_16x16x32_bf16 v[98:101], v[158:161], v[188:191], v[98:101]
	v_mfma_f32_16x16x32_bf16 v[86:89], v[150:153], v[196:199], v[86:89]
	v_mfma_f32_16x16x32_bf16 v[82:85], v[158:161], v[196:199], v[82:85]
	v_mfma_f32_16x16x32_bf16 v[70:73], v[150:153], v[204:207], v[70:73]
	v_mfma_f32_16x16x32_bf16 v[66:69], v[158:161], v[204:207], v[66:69]
	s_setprio 0
	s_barrier
	s_add_i32 s88, s81, s73
	s_mov_b64 s[16:17], s[26:27]
	s_mov_b32 m0, s88
	ds_read_b128 v[166:169], v182 offset:16384
	ds_read_b128 v[170:173], v182 offset:17408
	ds_read_b128 v[184:187], v182 offset:18432
	ds_read_b128 v[188:191], v182 offset:19456
	ds_read_b128 v[192:195], v182 offset:20480
	ds_read_b128 v[196:199], v182 offset:21504
	ds_read_b128 v[200:203], v182 offset:22528
	ds_read_b128 v[204:207], v182 offset:23552
	s_nop 0
	global_load_lds_dwordx4 v174, s[16:17]
	s_add_i32 m0, s88, 0x2000
	s_nop 0
	global_load_lds_dwordx4 v176, s[16:17]
	s_add_u32 s16, s26, 0x100000
	s_addc_u32 s17, s27, 0
	s_add_i32 s88, s82, s73
	s_mov_b32 m0, s88
	s_nop 0
	global_load_lds_dwordx4 v174, s[16:17]
	s_add_i32 m0, s88, 0x2000
	s_nop 0
	global_load_lds_dwordx4 v176, s[16:17]
	s_mov_b64 s[16:17], s[28:29]
	s_mov_b32 m0, s69
	s_nop 0
	global_load_lds_dwordx4 v1, s[16:17]
	s_mov_b32 m0, s71
	s_nop 0
	global_load_lds_dwordx4 v175, s[16:17]
	s_waitcnt vmcnt(8)
	s_waitcnt lgkmcnt(0)
	s_setprio 1
	s_waitcnt lgkmcnt(0)
	s_barrier
	v_mfma_f32_16x16x32_bf16 v[62:65], v[130:133], v[166:169], v[62:65]
	v_mfma_f32_16x16x32_bf16 v[58:61], v[138:141], v[166:169], v[58:61]
	v_mfma_f32_16x16x32_bf16 v[46:49], v[130:133], v[184:187], v[46:49]
	v_mfma_f32_16x16x32_bf16 v[42:45], v[138:141], v[184:187], v[42:45]
	v_mfma_f32_16x16x32_bf16 v[30:33], v[130:133], v[192:195], v[30:33]
	v_mfma_f32_16x16x32_bf16 v[26:29], v[138:141], v[192:195], v[26:29]
	v_mfma_f32_16x16x32_bf16 v[14:17], v[130:133], v[200:203], v[14:17]
	v_mfma_f32_16x16x32_bf16 v[10:13], v[138:141], v[200:203], v[10:13]
	v_mfma_f32_16x16x32_bf16 v[54:57], v[146:149], v[166:169], v[54:57]
	v_mfma_f32_16x16x32_bf16 v[50:53], v[154:157], v[166:169], v[50:53]
	v_mfma_f32_16x16x32_bf16 v[38:41], v[146:149], v[184:187], v[38:41]
	v_mfma_f32_16x16x32_bf16 v[34:37], v[154:157], v[184:187], v[34:37]
	v_mfma_f32_16x16x32_bf16 v[22:25], v[146:149], v[192:195], v[22:25]
	v_mfma_f32_16x16x32_bf16 v[18:21], v[154:157], v[192:195], v[18:21]
	v_mfma_f32_16x16x32_bf16 v[6:9], v[146:149], v[200:203], v[6:9]
	v_mfma_f32_16x16x32_bf16 v[2:5], v[154:157], v[200:203], v[2:5]
	v_mfma_f32_16x16x32_bf16 v[62:65], v[134:137], v[170:173], v[62:65]
	v_mfma_f32_16x16x32_bf16 v[58:61], v[142:145], v[170:173], v[58:61]
	v_mfma_f32_16x16x32_bf16 v[46:49], v[134:137], v[188:191], v[46:49]
	v_mfma_f32_16x16x32_bf16 v[42:45], v[142:145], v[188:191], v[42:45]
	v_mfma_f32_16x16x32_bf16 v[30:33], v[134:137], v[196:199], v[30:33]
	v_mfma_f32_16x16x32_bf16 v[26:29], v[142:145], v[196:199], v[26:29]
	v_mfma_f32_16x16x32_bf16 v[14:17], v[134:137], v[204:207], v[14:17]
	v_mfma_f32_16x16x32_bf16 v[10:13], v[142:145], v[204:207], v[10:13]
	v_mfma_f32_16x16x32_bf16 v[54:57], v[150:153], v[170:173], v[54:57]
	v_mfma_f32_16x16x32_bf16 v[50:53], v[158:161], v[170:173], v[50:53]
	v_mfma_f32_16x16x32_bf16 v[38:41], v[150:153], v[188:191], v[38:41]
	v_mfma_f32_16x16x32_bf16 v[34:37], v[158:161], v[188:191], v[34:37]
	v_mfma_f32_16x16x32_bf16 v[22:25], v[150:153], v[196:199], v[22:25]
	v_mfma_f32_16x16x32_bf16 v[18:21], v[158:161], v[196:199], v[18:21]
	v_mfma_f32_16x16x32_bf16 v[6:9], v[150:153], v[204:207], v[6:9]
	v_mfma_f32_16x16x32_bf16 v[2:5], v[158:161], v[204:207], v[2:5]
	s_setprio 0
	s_barrier
; #define PG8_STAGE(bufoff, gbase, voff) do { const char* _gb = (const char*)(gbase); asm volatile("" : "+s"(_gb)); _Pragma("unroll") for (int _i = 0; _i < 2; ++_i) { asm volatile("" : "+v"((voff)[_i])); \
;         __builtin_amdgcn_global_load_lds((const unsigned*)(_gb + (voff)[_i]), (PG8_LAS unsigned*)(lds + (bufoff) + ldsw + _i * 8192), 16, 0, 0); } } while (0)
; #define PG8_LDA(dst, b, h) do { _Pragma("unroll") for (int m = 0; m < 4; ++m) _Pragma("unroll") for (int k = 0; k < 2; ++k) dst[m][k] = *(const PG8_LAS bf16x8*)(lds + PG8_SA(b, h) + aoff + m * 2048 + k * 1024); } while (0)
; #define PG8_LDB(dst, b, h) do { _Pragma("unroll") for (int n = 0; n < 2; ++n) _Pragma("unroll") for (int k = 0; k < 2; ++k) dst[n][k] = *(const PG8_LAS bf16x8*)(lds + PG8_SB(b, h) + boff + n * 2048 + k * 1024); } while (0)
; #define PG8_WAIT_V(n) asm volatile("s_waitcnt vmcnt(" #n ")" ::: "memory")
; #define PG8_WAIT_L(n) asm volatile("s_waitcnt lgkmcnt(" #n ")" ::: "memory")
; #define PG8_BAR __builtin_amdgcn_s_barrier()
; #define PG8_SCHED __builtin_amdgcn_sched_barrier(0)
; #define PG8_STAGE(bufoff, gbase, voff) do { const char* _gb = (const char*)(gbase); asm volatile("" : "+s"(_gb)); _Pragma("unroll") for (int _i = 0; _i < 2; ++_i) { asm volatile("" : "+v"((voff)[_i])); \
;         __builtin_amdgcn_global_load_lds((const unsigned*)(_gb + (voff)[_i]), (PG8_LAS unsigned*)(lds + (bufoff) + ldsw + _i * 8192), 16, 0, 0); } } while (0)
; #define PG8_LDA(dst, b, h) do { _Pragma("unroll") for (int m = 0; m < 4; ++m) _Pragma("unroll") for (int k = 0; k < 2; ++k) dst[m][k] = *(const PG8_LAS bf16x8*)(lds + PG8_SA(b, h) + aoff + m * 2048 + k * 1024); } while (0)
; #define PG8_WAIT_V(n) asm volatile("s_waitcnt vmcnt(" #n ")" ::: "memory")
; template <class Epi, class Sched, bool ALIGN_EPI = false, bool SP2 = false>
; __device__ __forceinline__ void gemm_phase(PG8_LAS unsigned char* lds, const Gemm g, const Sched& S, const Epi& E) {
;     ...
;             PG8_LDB(B0, 1, 0); PG8_LDB(B1, 1, 1); PG8_SCHED; PG8_LDA(At, 1, 0); PG8_STAGE(PG8_SA(0, 1), a2 + hstep, voffA);
;             PG8_WAIT_V(8); PG8_WAIT_L(0); PG8_BAR; PG8_MMA2(0); PG8_BAR; PG8_SCHED;
;             PG8_LDA(At, 1, 1); PG8_STAGE(PG8_SB(1, 0), b3, voffB); PG8_STAGE(PG8_SB(1, 1), b3 + hstep, voffB); PG8_STAGE(PG8_SA(1, 0), a3, voffA);
;             PG8_WAIT_V(8); PG8_WAIT_L(0); PG8_BAR; PG8_MMA2(1); PG8_BAR; PG8_SCHED;
	s_add_i32 s88, 0, 0x18000
	s_add_i32 s89, 0, 0x1c000
	ds_read_b128 v[130:133], v239
	ds_read_b128 v[134:137], v239 offset:1024
	ds_read_b128 v[138:141], v239 offset:2048
	ds_read_b128 v[142:145], v239 offset:3072
	ds_read_b128 v[146:149], v240
	ds_read_b128 v[150:153], v240 offset:1024
	ds_read_b128 v[154:157], v240 offset:2048
	ds_read_b128 v[158:161], v240 offset:3072
	s_add_u32 s16, s28, 0x100000
	s_addc_u32 s17, s29, 0
	s_mov_b32 m0, s74
	ds_read_b128 v[166:169], v182 offset:32768
	ds_read_b128 v[170:173], v182 offset:33792
	ds_read_b128 v[184:187], v182 offset:34816
	ds_read_b128 v[188:191], v182 offset:35840
	ds_read_b128 v[192:195], v182 offset:36864
	ds_read_b128 v[196:199], v182 offset:37888
	ds_read_b128 v[200:203], v182 offset:38912
	ds_read_b128 v[204:207], v182 offset:39936
	s_nop 0
	global_load_lds_dwordx4 v1, s[16:17]
	s_mov_b32 m0, s75
	s_nop 0
	global_load_lds_dwordx4 v175, s[16:17]
	s_waitcnt vmcnt(8)
	s_waitcnt lgkmcnt(0)
	s_setprio 1
	s_waitcnt lgkmcnt(0)
	s_barrier
	v_mfma_f32_16x16x32_bf16 v[126:129], v[130:133], v[166:169], v[126:129]
	v_mfma_f32_16x16x32_bf16 v[122:125], v[138:141], v[166:169], v[122:125]
	v_mfma_f32_16x16x32_bf16 v[110:113], v[130:133], v[184:187], v[110:113]
	v_mfma_f32_16x16x32_bf16 v[106:109], v[138:141], v[184:187], v[106:109]
	v_mfma_f32_16x16x32_bf16 v[94:97], v[130:133], v[192:195], v[94:97]
	v_mfma_f32_16x16x32_bf16 v[90:93], v[138:141], v[192:195], v[90:93]
	v_mfma_f32_16x16x32_bf16 v[78:81], v[130:133], v[200:203], v[78:81]
	v_mfma_f32_16x16x32_bf16 v[74:77], v[138:141], v[200:203], v[74:77]
	v_mfma_f32_16x16x32_bf16 v[118:121], v[146:149], v[166:169], v[118:121]
	v_mfma_f32_16x16x32_bf16 v[114:117], v[154:157], v[166:169], v[114:117]
	v_mfma_f32_16x16x32_bf16 v[102:105], v[146:149], v[184:187], v[102:105]
	v_mfma_f32_16x16x32_bf16 v[98:101], v[154:157], v[184:187], v[98:101]
	v_mfma_f32_16x16x32_bf16 v[86:89], v[146:149], v[192:195], v[86:89]
	v_mfma_f32_16x16x32_bf16 v[82:85], v[154:157], v[192:195], v[82:85]
	v_mfma_f32_16x16x32_bf16 v[70:73], v[146:149], v[200:203], v[70:73]
	v_mfma_f32_16x16x32_bf16 v[66:69], v[154:157], v[200:203], v[66:69]
	v_mfma_f32_16x16x32_bf16 v[126:129], v[134:137], v[170:173], v[126:129]
	v_mfma_f32_16x16x32_bf16 v[122:125], v[142:145], v[170:173], v[122:125]
	v_mfma_f32_16x16x32_bf16 v[110:113], v[134:137], v[188:191], v[110:113]
	v_mfma_f32_16x16x32_bf16 v[106:109], v[142:145], v[188:191], v[106:109]
	v_mfma_f32_16x16x32_bf16 v[94:97], v[134:137], v[196:199], v[94:97]
	v_mfma_f32_16x16x32_bf16 v[90:93], v[142:145], v[196:199], v[90:93]
	v_mfma_f32_16x16x32_bf16 v[78:81], v[134:137], v[204:207], v[78:81]
	v_mfma_f32_16x16x32_bf16 v[74:77], v[142:145], v[204:207], v[74:77]
	v_mfma_f32_16x16x32_bf16 v[118:121], v[150:153], v[170:173], v[118:121]
	v_mfma_f32_16x16x32_bf16 v[114:117], v[158:161], v[170:173], v[114:117]
	v_mfma_f32_16x16x32_bf16 v[102:105], v[150:153], v[188:191], v[102:105]
	v_mfma_f32_16x16x32_bf16 v[98:101], v[158:161], v[188:191], v[98:101]
	v_mfma_f32_16x16x32_bf16 v[86:89], v[150:153], v[196:199], v[86:89]
	v_mfma_f32_16x16x32_bf16 v[82:85], v[158:161], v[196:199], v[82:85]
	v_mfma_f32_16x16x32_bf16 v[70:73], v[150:153], v[204:207], v[70:73]
	v_mfma_f32_16x16x32_bf16 v[66:69], v[158:161], v[204:207], v[66:69]
	s_setprio 0
	s_barrier
	s_add_u32 s16, s26, 0x80
	s_addc_u32 s17, s27, 0
	s_add_i32 s28, s88, s73
	s_mov_b32 m0, s28
	ds_read_b128 v[166:169], v182 offset:49152
	ds_read_b128 v[170:173], v182 offset:50176
	ds_read_b128 v[184:187], v182 offset:51200
	ds_read_b128 v[188:191], v182 offset:52224
	ds_read_b128 v[192:195], v182 offset:53248
	ds_read_b128 v[196:199], v182 offset:54272
	ds_read_b128 v[200:203], v182 offset:55296
	ds_read_b128 v[204:207], v182 offset:56320
	s_nop 0
	global_load_lds_dwordx4 v174, s[16:17]
	s_add_i32 m0, s28, 0x2000
	s_nop 0
	global_load_lds_dwordx4 v176, s[16:17]
	s_add_u32 s16, s26, 0x100080
	s_addc_u32 s17, s27, 0
	s_add_i32 s26, s89, s73
	s_mov_b32 m0, s26
	s_nop 0
	global_load_lds_dwordx4 v174, s[16:17]
	s_add_i32 m0, s26, 0x2000
	s_nop 0
	global_load_lds_dwordx4 v176, s[16:17]
	s_mov_b32 m0, s77
	s_nop 0
	global_load_lds_dwordx4 v1, s[2:3]
	s_mov_b32 m0, s78
	s_nop 0
	global_load_lds_dwordx4 v175, s[2:3]
	s_waitcnt vmcnt(8)
	s_waitcnt lgkmcnt(0)
	s_setprio 1
	s_waitcnt lgkmcnt(0)
	s_barrier
	v_mfma_f32_16x16x32_bf16 v[62:65], v[130:133], v[166:169], v[62:65]
	v_mfma_f32_16x16x32_bf16 v[58:61], v[138:141], v[166:169], v[58:61]
	v_mfma_f32_16x16x32_bf16 v[46:49], v[130:133], v[184:187], v[46:49]
	v_mfma_f32_16x16x32_bf16 v[42:45], v[138:141], v[184:187], v[42:45]
	v_mfma_f32_16x16x32_bf16 v[30:33], v[130:133], v[192:195], v[30:33]
	v_mfma_f32_16x16x32_bf16 v[26:29], v[138:141], v[192:195], v[26:29]
	v_mfma_f32_16x16x32_bf16 v[14:17], v[130:133], v[200:203], v[14:17]
	v_mfma_f32_16x16x32_bf16 v[10:13], v[138:141], v[200:203], v[10:13]
	v_mfma_f32_16x16x32_bf16 v[54:57], v[146:149], v[166:169], v[54:57]
	v_mfma_f32_16x16x32_bf16 v[50:53], v[154:157], v[166:169], v[50:53]
	v_mfma_f32_16x16x32_bf16 v[38:41], v[146:149], v[184:187], v[38:41]
	v_mfma_f32_16x16x32_bf16 v[34:37], v[154:157], v[184:187], v[34:37]
	v_mfma_f32_16x16x32_bf16 v[22:25], v[146:149], v[192:195], v[22:25]
	v_mfma_f32_16x16x32_bf16 v[18:21], v[154:157], v[192:195], v[18:21]
	v_mfma_f32_16x16x32_bf16 v[6:9], v[146:149], v[200:203], v[6:9]
	v_mfma_f32_16x16x32_bf16 v[2:5], v[154:157], v[200:203], v[2:5]
	v_mfma_f32_16x16x32_bf16 v[62:65], v[134:137], v[170:173], v[62:65]
	v_mfma_f32_16x16x32_bf16 v[58:61], v[142:145], v[170:173], v[58:61]
	v_mfma_f32_16x16x32_bf16 v[46:49], v[134:137], v[188:191], v[46:49]
	v_mfma_f32_16x16x32_bf16 v[42:45], v[142:145], v[188:191], v[42:45]
	v_mfma_f32_16x16x32_bf16 v[30:33], v[134:137], v[196:199], v[30:33]
	v_mfma_f32_16x16x32_bf16 v[26:29], v[142:145], v[196:199], v[26:29]
	v_mfma_f32_16x16x32_bf16 v[14:17], v[134:137], v[204:207], v[14:17]
	v_mfma_f32_16x16x32_bf16 v[10:13], v[142:145], v[204:207], v[10:13]
	v_mfma_f32_16x16x32_bf16 v[54:57], v[150:153], v[170:173], v[54:57]
	v_mfma_f32_16x16x32_bf16 v[50:53], v[158:161], v[170:173], v[50:53]
	v_mfma_f32_16x16x32_bf16 v[38:41], v[150:153], v[188:191], v[38:41]
	v_mfma_f32_16x16x32_bf16 v[34:37], v[158:161], v[188:191], v[34:37]
	v_mfma_f32_16x16x32_bf16 v[22:25], v[150:153], v[196:199], v[22:25]
	v_mfma_f32_16x16x32_bf16 v[18:21], v[158:161], v[196:199], v[18:21]
	v_mfma_f32_16x16x32_bf16 v[6:9], v[150:153], v[204:207], v[6:9]
	v_mfma_f32_16x16x32_bf16 v[2:5], v[158:161], v[204:207], v[2:5]
	s_setprio 0
	s_barrier
	s_add_i32 s87, s87, 2
	s_add_u32 s85, s85, 0x100
	s_addc_u32 s86, s86, 0
	s_cmp_gt_u32 s87, 61
	s_mov_b64 s[16:17], s[24:25]
	s_cbranch_scc0 .LBB0_833
	s_and_b64 vcc, exec, s[12:13]
	s_cbranch_vccz .LBB0_836
	s_barrier

;     __device__ bool next(int i, Unit& u) const { if (i > 1) return false; const int xcd = c & 7, idx = c >> 3; u.pm = 16 * i + 4 * (xcd >> 1) + (idx & 3); u.pn = 8 * (xcd & 1) + (idx >> 2); return true; }
; #define PG8_STAGE(bufoff, gbase, voff) do { const char* _gb = (const char*)(gbase); asm volatile("" : "+s"(_gb)); _Pragma("unroll") for (int _i = 0; _i < 2; ++_i) { asm volatile("" : "+v"((voff)[_i])); \
;         __builtin_amdgcn_global_load_lds((const unsigned*)(_gb + (voff)[_i]), (PG8_LAS unsigned*)(lds + (bufoff) + ldsw + _i * 8192), 16, 0, 0); } } while (0)
; #define PG8_LDA(dst, b, h) do { _Pragma("unroll") for (int m = 0; m < 4; ++m) _Pragma("unroll") for (int k = 0; k < 2; ++k) dst[m][k] = *(const PG8_LAS bf16x8*)(lds + PG8_SA(b, h) + aoff + m * 2048 + k * 1024); } while (0)
; #define PG8_LDB(dst, b, h) do { _Pragma("unroll") for (int n = 0; n < 2; ++n) _Pragma("unroll") for (int k = 0; k < 2; ++k) dst[n][k] = *(const PG8_LAS bf16x8*)(lds + PG8_SB(b, h) + boff + n * 2048 + k * 1024); } while (0)
; #define PG8_SCHED __builtin_amdgcn_sched_barrier(0)
; template <class Epi, class Sched, bool ALIGN_EPI = false, bool SP2 = false>
; __device__ __forceinline__ void gemm_phase(PG8_LAS unsigned char* lds, const Gemm g, const Sched& S, const Epi& E) {
;     ...
;         const bool has_next = S.next(ui + 1, nxt);
;         const char* nA = has_next ? (const char*)g.A + (size_t)nxt.pm * tstep : cA; const char* nB = has_next ? (const char*)g.Bt + (size_t)nxt.pn * tstep : cB;
;         for (int t = 0; t < nt; t += 2) {
;             const bool last = (t == nt - 2);
;             const char* a1 = cA + (size_t)(t + 1) * kstep;
;             const char* a2 = last ? nA : cA + (size_t)(t + 2) * kstep; const char* b2 = last ? nB : cB + (size_t)(t + 2) * kstep;
;             const char* a3 = a2 + kstep; const char* b3 = b2 + kstep;
;             if (last && has_next) S.a_ready(nxt);
;             if constexpr (SP2) {
;             PG8_LDB(B0, 0, 0); PG8_LDB(B1, 0, 1); PG8_SCHED; PG8_LDA(At, 0, 0); PG8_STAGE(PG8_SA(1, 1), a1 + hstep, voffA);
;     ...
; #pragma unroll
;         for (int a = 0; a < 2; ++a)
; #pragma unroll
;             for (int b = 0; b < 2; ++b)
; #pragma unroll
;                 for (int m = 0; m < 4; ++m)
; #pragma unroll
;                     for (int n = 0; n < 2; ++n) acc[a][b][m][n] = (f32x4){0.f, 0.f, 0.f, 0.f};
;         cur = nxt; cA = nA; cB = nB; ++ui;
.LBB0_932:
	s_ashr_i32 s51, s50, 31
	s_lshl_b64 s[2:3], s[50:51], 21
	s_add_u32 s52, s26, s2
	s_addc_u32 s53, s27, s3
	s_and_b64 s[2:3], s[10:11], exec
	s_cselect_b32 s20, s53, s13
	s_cselect_b32 s21, s52, s12
	s_ashr_i32 s49, s48, 31
	s_lshl_b64 s[2:3], s[48:49], 21
	s_add_u32 s54, s28, s2
	s_addc_u32 s55, s29, s3
	s_and_b64 s[2:3], s[10:11], exec
	s_cselect_b32 s49, s55, s15
	s_cselect_b32 s51, s54, s14
	s_add_u32 s62, s14, 0x100
	v_mov_b32_e32 v38, 0
	s_addc_u32 s63, s15, 0
	s_mov_b32 s83, -2
	v_mov_b32_e32 v39, v38
	v_mov_b32_e32 v40, v38
	v_mov_b32_e32 v41, v38
	v_mov_b32_e32 v42, v38
	v_mov_b32_e32 v43, v38
	v_mov_b32_e32 v44, v38
	v_mov_b32_e32 v45, v38
	v_mov_b32_e32 v46, v38
	v_mov_b32_e32 v47, v38
	v_mov_b32_e32 v48, v38
	v_mov_b32_e32 v49, v38
	v_mov_b32_e32 v54, v38
	v_mov_b32_e32 v55, v38
	v_mov_b32_e32 v56, v38
	v_mov_b32_e32 v57, v38
	v_mov_b32_e32 v2, v38
	v_mov_b32_e32 v3, v38
	v_mov_b32_e32 v4, v38
	v_mov_b32_e32 v5, v38
	v_mov_b32_e32 v10, v38
	v_mov_b32_e32 v11, v38
	v_mov_b32_e32 v12, v38
	v_mov_b32_e32 v13, v38
	v_mov_b32_e32 v14, v38
	v_mov_b32_e32 v15, v38
	v_mov_b32_e32 v16, v38
	v_mov_b32_e32 v17, v38
	v_mov_b32_e32 v18, v38
	v_mov_b32_e32 v19, v38
	v_mov_b32_e32 v20, v38
	v_mov_b32_e32 v21, v38
	v_mov_b32_e32 v50, v38
	v_mov_b32_e32 v51, v38
	v_mov_b32_e32 v52, v38
	v_mov_b32_e32 v53, v38
	v_mov_b32_e32 v58, v38
	v_mov_b32_e32 v59, v38
	v_mov_b32_e32 v60, v38
	v_mov_b32_e32 v61, v38
	v_mov_b32_e32 v66, v38
	v_mov_b32_e32 v67, v38
	v_mov_b32_e32 v68, v38
	v_mov_b32_e32 v69, v38
	v_mov_b32_e32 v70, v38
	v_mov_b32_e32 v71, v38
	v_mov_b32_e32 v72, v38
	v_mov_b32_e32 v73, v38
	v_mov_b32_e32 v22, v38
	v_mov_b32_e32 v23, v38
	v_mov_b32_e32 v24, v38
	v_mov_b32_e32 v25, v38
	v_mov_b32_e32 v26, v38
	v_mov_b32_e32 v27, v38
	v_mov_b32_e32 v28, v38
	v_mov_b32_e32 v29, v38
	v_mov_b32_e32 v30, v38
	v_mov_b32_e32 v31, v38
	v_mov_b32_e32 v32, v38
	v_mov_b32_e32 v33, v38
	v_mov_b32_e32 v34, v38
	v_mov_b32_e32 v35, v38
	v_mov_b32_e32 v36, v38
	v_mov_b32_e32 v37, v38
	v_mov_b32_e32 v102, v38
	v_mov_b32_e32 v103, v38
	v_mov_b32_e32 v104, v38
	v_mov_b32_e32 v105, v38
	v_mov_b32_e32 v122, v38
	v_mov_b32_e32 v123, v38
	v_mov_b32_e32 v124, v38
	v_mov_b32_e32 v125, v38
	v_mov_b32_e32 v98, v38
	v_mov_b32_e32 v99, v38
	v_mov_b32_e32 v100, v38
	v_mov_b32_e32 v101, v38
	v_mov_b32_e32 v126, v38
	v_mov_b32_e32 v127, v38
	v_mov_b32_e32 v128, v38
	v_mov_b32_e32 v129, v38
	v_mov_b32_e32 v74, v38
	v_mov_b32_e32 v75, v38
	v_mov_b32_e32 v76, v38
	v_mov_b32_e32 v77, v38
	v_mov_b32_e32 v78, v38
	v_mov_b32_e32 v79, v38
	v_mov_b32_e32 v80, v38
	v_mov_b32_e32 v81, v38
	v_mov_b32_e32 v82, v38
	v_mov_b32_e32 v83, v38
	v_mov_b32_e32 v84, v38
	v_mov_b32_e32 v85, v38
	v_mov_b32_e32 v94, v38
	v_mov_b32_e32 v95, v38
	v_mov_b32_e32 v96, v38
	v_mov_b32_e32 v97, v38
	v_mov_b32_e32 v110, v38
	v_mov_b32_e32 v111, v38
	v_mov_b32_e32 v112, v38
	v_mov_b32_e32 v113, v38
	v_mov_b32_e32 v130, v38
	v_mov_b32_e32 v131, v38
	v_mov_b32_e32 v132, v38
	v_mov_b32_e32 v133, v38
	v_mov_b32_e32 v90, v38
	v_mov_b32_e32 v91, v38
	v_mov_b32_e32 v92, v38
	v_mov_b32_e32 v93, v38
	v_mov_b32_e32 v134, v38
	v_mov_b32_e32 v135, v38
	v_mov_b32_e32 v136, v38
	v_mov_b32_e32 v137, v38
	v_mov_b32_e32 v86, v38
	v_mov_b32_e32 v87, v38
	v_mov_b32_e32 v88, v38
	v_mov_b32_e32 v89, v38
	v_mov_b32_e32 v106, v38
	v_mov_b32_e32 v107, v38
	v_mov_b32_e32 v108, v38
	v_mov_b32_e32 v109, v38
	v_mov_b32_e32 v114, v38
	v_mov_b32_e32 v115, v38
	v_mov_b32_e32 v116, v38
	v_mov_b32_e32 v117, v38
	v_mov_b32_e32 v118, v38
	v_mov_b32_e32 v119, v38
	v_mov_b32_e32 v120, v38
	v_mov_b32_e32 v121, v38
	v_add_u32_e32 v239, 0x10000, v201
	v_add_u32_e32 v240, 0x14000, v201
	v_add_u32_e32 v241, 0x18000, v201
	v_add_u32_e32 v242, 0x1c000, v201
.LBB0_933:
	s_nop 0
	ds_read_b128 v[6:9], v239
	ds_read_b128 v[62:65], v239 offset:1024
	ds_read_b128 v[138:141], v239 offset:2048
	ds_read_b128 v[142:145], v239 offset:3072
	ds_read_b128 v[164:167], v240
	ds_read_b128 v[168:171], v240 offset:1024
	ds_read_b128 v[172:175], v240 offset:2048
	ds_read_b128 v[176:179], v240 offset:3072
	s_add_u32 s14, s12, 0x100
	s_addc_u32 s15, s13, 0
	s_cmp_eq_u32 s83, 60
	s_cselect_b32 s18, s21, s14
	s_cselect_b32 s19, s20, s15
	s_cselect_b32 s16, s51, s62
	s_cselect_b32 s17, s49, s63
	s_add_u32 s2, s18, 0x80
	s_addc_u32 s3, s19, 0
	s_add_u32 s12, s12, 0x100080
	s_addc_u32 s13, s13, 0
	s_add_i32 m0, s33, 0xc000
	ds_read_b128 v[180:183], v219
	ds_read_b128 v[184:187], v219 offset:1024
	ds_read_b128 v[188:191], v219 offset:2048
	ds_read_b128 v[192:195], v219 offset:3072
	ds_read_b128 v[222:225], v219 offset:4096
	ds_read_b128 v[226:229], v219 offset:5120
	ds_read_b128 v[230:233], v219 offset:6144
	ds_read_b128 v[234:237], v219 offset:7168
	s_nop 0
	global_load_lds_dwordx4 v1, s[12:13]
	s_add_i32 m0, s33, 0xe000
	s_nop 0
	global_load_lds_dwordx4 v199, s[12:13]
	s_waitcnt vmcnt(8)
	s_waitcnt lgkmcnt(0)
	s_setprio 1
	s_waitcnt lgkmcnt(0)
	s_barrier
; #define PG8_STAGE(bufoff, gbase, voff) do { const char* _gb = (const char*)(gbase); asm volatile("" : "+s"(_gb)); _Pragma("unroll") for (int _i = 0; _i < 2; ++_i) { asm volatile("" : "+v"((voff)[_i])); \
;         __builtin_amdgcn_global_load_lds((const unsigned*)(_gb + (voff)[_i]), (PG8_LAS unsigned*)(lds + (bufoff) + ldsw + _i * 8192), 16, 0, 0); } } while (0)
; #define PG8_LDA(dst, b, h) do { _Pragma("unroll") for (int m = 0; m < 4; ++m) _Pragma("unroll") for (int k = 0; k < 2; ++k) dst[m][k] = *(const PG8_LAS bf16x8*)(lds + PG8_SA(b, h) + aoff + m * 2048 + k * 1024); } while (0)
; #define PG8_LDB(dst, b, h) do { _Pragma("unroll") for (int n = 0; n < 2; ++n) _Pragma("unroll") for (int k = 0; k < 2; ++k) dst[n][k] = *(const PG8_LAS bf16x8*)(lds + PG8_SB(b, h) + boff + n * 2048 + k * 1024); } while (0)
; #define PG8_WAIT_V(n) asm volatile("s_waitcnt vmcnt(" #n ")" ::: "memory")
; #define PG8_WAIT_L(n) asm volatile("s_waitcnt lgkmcnt(" #n ")" ::: "memory")
; #define PG8_BAR __builtin_amdgcn_s_barrier()
; #define PG8_SCHED __builtin_amdgcn_sched_barrier(0)
; #define PG8_STAGE(bufoff, gbase, voff) do { const char* _gb = (const char*)(gbase); asm volatile("" : "+s"(_gb)); _Pragma("unroll") for (int _i = 0; _i < 2; ++_i) { asm volatile("" : "+v"((voff)[_i])); \
;         __builtin_amdgcn_global_load_lds((const unsigned*)(_gb + (voff)[_i]), (PG8_LAS unsigned*)(lds + (bufoff) + ldsw + _i * 8192), 16, 0, 0); } } while (0)
; #define PG8_LDA(dst, b, h) do { _Pragma("unroll") for (int m = 0; m < 4; ++m) _Pragma("unroll") for (int k = 0; k < 2; ++k) dst[m][k] = *(const PG8_LAS bf16x8*)(lds + PG8_SA(b, h) + aoff + m * 2048 + k * 1024); } while (0)
; #define PG8_WAIT_V(n) asm volatile("s_waitcnt vmcnt(" #n ")" ::: "memory")
; template <class Epi, class Sched, bool ALIGN_EPI = false, bool SP2 = false>
; __device__ __forceinline__ void gemm_phase(PG8_LAS unsigned char* lds, const Gemm g, const Sched& S, const Epi& E) {
;     ...
;             PG8_LDB(B0, 0, 0); PG8_LDB(B1, 0, 1); PG8_SCHED; PG8_LDA(At, 0, 0); PG8_STAGE(PG8_SA(1, 1), a1 + hstep, voffA);
;             PG8_WAIT_V(8); PG8_WAIT_L(0); PG8_BAR; PG8_MMA2(0); PG8_BAR; PG8_SCHED;
;             PG8_LDA(At, 0, 1); PG8_STAGE(PG8_SB(0, 0), b2, voffB); PG8_STAGE(PG8_SB(0, 1), b2 + hstep, voffB); PG8_STAGE(PG8_SA(0, 0), a2, voffA);
;             PG8_WAIT_V(8); PG8_WAIT_L(0); PG8_BAR; PG8_MMA2(1); PG8_BAR; PG8_SCHED;
	v_mfma_f32_16x16x32_bf16 v[118:121], v[6:9], v[180:183], v[118:121]
	v_mfma_f32_16x16x32_bf16 v[114:117], v[138:141], v[180:183], v[114:117]
	v_mfma_f32_16x16x32_bf16 v[106:109], v[6:9], v[188:191], v[106:109]
	v_mfma_f32_16x16x32_bf16 v[86:89], v[138:141], v[188:191], v[86:89]
	v_mfma_f32_16x16x32_bf16 v[134:137], v[6:9], v[222:225], v[134:137]
	v_mfma_f32_16x16x32_bf16 v[90:93], v[138:141], v[222:225], v[90:93]
	v_mfma_f32_16x16x32_bf16 v[130:133], v[6:9], v[230:233], v[130:133]
	v_mfma_f32_16x16x32_bf16 v[110:113], v[138:141], v[230:233], v[110:113]
	v_mfma_f32_16x16x32_bf16 v[94:97], v[164:167], v[180:183], v[94:97]
	v_mfma_f32_16x16x32_bf16 v[82:85], v[172:175], v[180:183], v[82:85]
	v_mfma_f32_16x16x32_bf16 v[78:81], v[164:167], v[188:191], v[78:81]
	v_mfma_f32_16x16x32_bf16 v[74:77], v[172:175], v[188:191], v[74:77]
	v_mfma_f32_16x16x32_bf16 v[126:129], v[164:167], v[222:225], v[126:129]
	v_mfma_f32_16x16x32_bf16 v[98:101], v[172:175], v[222:225], v[98:101]
	v_mfma_f32_16x16x32_bf16 v[122:125], v[164:167], v[230:233], v[122:125]
	v_mfma_f32_16x16x32_bf16 v[102:105], v[172:175], v[230:233], v[102:105]
	v_mfma_f32_16x16x32_bf16 v[118:121], v[62:65], v[184:187], v[118:121]
	v_mfma_f32_16x16x32_bf16 v[114:117], v[142:145], v[184:187], v[114:117]
	v_mfma_f32_16x16x32_bf16 v[106:109], v[62:65], v[192:195], v[106:109]
	v_mfma_f32_16x16x32_bf16 v[86:89], v[142:145], v[192:195], v[86:89]
	v_mfma_f32_16x16x32_bf16 v[134:137], v[62:65], v[226:229], v[134:137]
	v_mfma_f32_16x16x32_bf16 v[90:93], v[142:145], v[226:229], v[90:93]
	v_mfma_f32_16x16x32_bf16 v[130:133], v[62:65], v[234:237], v[130:133]
	v_mfma_f32_16x16x32_bf16 v[110:113], v[142:145], v[234:237], v[110:113]
	v_mfma_f32_16x16x32_bf16 v[94:97], v[168:171], v[184:187], v[94:97]
	v_mfma_f32_16x16x32_bf16 v[82:85], v[176:179], v[184:187], v[82:85]
	v_mfma_f32_16x16x32_bf16 v[78:81], v[168:171], v[192:195], v[78:81]
	v_mfma_f32_16x16x32_bf16 v[74:77], v[176:179], v[192:195], v[74:77]
	v_mfma_f32_16x16x32_bf16 v[126:129], v[168:171], v[226:229], v[126:129]
	v_mfma_f32_16x16x32_bf16 v[98:101], v[176:179], v[226:229], v[98:101]
	v_mfma_f32_16x16x32_bf16 v[122:125], v[168:171], v[234:237], v[122:125]
	v_mfma_f32_16x16x32_bf16 v[102:105], v[176:179], v[234:237], v[102:105]
	s_setprio 0
	s_barrier
	s_add_i32 s84, s78, s25
	s_mov_b64 s[12:13], s[16:17]
	s_mov_b32 m0, s84
	ds_read_b128 v[180:183], v219 offset:16384
	ds_read_b128 v[184:187], v219 offset:17408
	ds_read_b128 v[188:191], v219 offset:18432
	ds_read_b128 v[192:195], v219 offset:19456
	ds_read_b128 v[222:225], v219 offset:20480
	ds_read_b128 v[226:229], v219 offset:21504
	ds_read_b128 v[230:233], v219 offset:22528
	ds_read_b128 v[234:237], v219 offset:23552
	s_nop 0
	global_load_lds_dwordx4 v198, s[12:13]
	s_add_i32 m0, s84, 0x2000
	s_nop 0
	global_load_lds_dwordx4 v200, s[12:13]
	s_add_u32 s12, s16, 0x100000
	s_addc_u32 s13, s17, 0
	s_add_i32 s84, s79, s25
	s_mov_b32 m0, s84
	s_nop 0
	global_load_lds_dwordx4 v198, s[12:13]
	s_add_i32 m0, s84, 0x2000
	s_nop 0
	global_load_lds_dwordx4 v200, s[12:13]
	s_mov_b64 s[12:13], s[18:19]
	s_mov_b32 m0, s33
	s_nop 0
	global_load_lds_dwordx4 v1, s[12:13]
	s_mov_b32 m0, s45
	s_nop 0
	global_load_lds_dwordx4 v199, s[12:13]
	s_waitcnt vmcnt(8)
	s_waitcnt lgkmcnt(0)
	s_setprio 1
	s_waitcnt lgkmcnt(0)
	s_barrier
	v_mfma_f32_16x16x32_bf16 v[34:37], v[6:9], v[180:183], v[34:37]
	v_mfma_f32_16x16x32_bf16 v[30:33], v[138:141], v[180:183], v[30:33]
	v_mfma_f32_16x16x32_bf16 v[26:29], v[6:9], v[188:191], v[26:29]
	v_mfma_f32_16x16x32_bf16 v[22:25], v[138:141], v[188:191], v[22:25]
	v_mfma_f32_16x16x32_bf16 v[70:73], v[6:9], v[222:225], v[70:73]
	v_mfma_f32_16x16x32_bf16 v[66:69], v[138:141], v[222:225], v[66:69]
	v_mfma_f32_16x16x32_bf16 v[50:53], v[138:141], v[230:233], v[50:53]
	v_mfma_f32_16x16x32_bf16 v[18:21], v[164:167], v[180:183], v[18:21]
	v_mfma_f32_16x16x32_bf16 v[14:17], v[172:175], v[180:183], v[14:17]
	v_mfma_f32_16x16x32_bf16 v[10:13], v[164:167], v[188:191], v[10:13]
	v_mfma_f32_16x16x32_bf16 v[2:5], v[172:175], v[188:191], v[2:5]
	v_mfma_f32_16x16x32_bf16 v[54:57], v[164:167], v[222:225], v[54:57]
	v_mfma_f32_16x16x32_bf16 v[46:49], v[172:175], v[222:225], v[46:49]
	v_mfma_f32_16x16x32_bf16 v[42:45], v[164:167], v[230:233], v[42:45]
	v_mfma_f32_16x16x32_bf16 v[38:41], v[172:175], v[230:233], v[38:41]
	v_mfma_f32_16x16x32_bf16 v[34:37], v[62:65], v[184:187], v[34:37]
	v_mfma_f32_16x16x32_bf16 v[30:33], v[142:145], v[184:187], v[30:33]
	v_mfma_f32_16x16x32_bf16 v[26:29], v[62:65], v[192:195], v[26:29]
	v_mfma_f32_16x16x32_bf16 v[22:25], v[142:145], v[192:195], v[22:25]
	v_mfma_f32_16x16x32_bf16 v[70:73], v[62:65], v[226:229], v[70:73]
	v_mfma_f32_16x16x32_bf16 v[66:69], v[142:145], v[226:229], v[66:69]
	v_mfma_f32_16x16x32_bf16 v[6:9], v[6:9], v[230:233], v[58:61]
	v_mfma_f32_16x16x32_bf16 v[50:53], v[142:145], v[234:237], v[50:53]
	v_mfma_f32_16x16x32_bf16 v[18:21], v[168:171], v[184:187], v[18:21]
	v_mfma_f32_16x16x32_bf16 v[14:17], v[176:179], v[184:187], v[14:17]
	v_mfma_f32_16x16x32_bf16 v[10:13], v[168:171], v[192:195], v[10:13]
	v_mfma_f32_16x16x32_bf16 v[2:5], v[176:179], v[192:195], v[2:5]
	v_mfma_f32_16x16x32_bf16 v[54:57], v[168:171], v[226:229], v[54:57]
	v_mfma_f32_16x16x32_bf16 v[46:49], v[176:179], v[226:229], v[46:49]
	v_mfma_f32_16x16x32_bf16 v[42:45], v[168:171], v[234:237], v[42:45]
	v_mfma_f32_16x16x32_bf16 v[38:41], v[176:179], v[234:237], v[38:41]
	v_mfma_f32_16x16x32_bf16 v[6:9], v[62:65], v[234:237], v[6:9]
	s_setprio 0
	s_barrier
; #define PG8_STAGE(bufoff, gbase, voff) do { const char* _gb = (const char*)(gbase); asm volatile("" : "+s"(_gb)); _Pragma("unroll") for (int _i = 0; _i < 2; ++_i) { asm volatile("" : "+v"((voff)[_i])); \
;         __builtin_amdgcn_global_load_lds((const unsigned*)(_gb + (voff)[_i]), (PG8_LAS unsigned*)(lds + (bufoff) + ldsw + _i * 8192), 16, 0, 0); } } while (0)
; #define PG8_LDA(dst, b, h) do { _Pragma("unroll") for (int m = 0; m < 4; ++m) _Pragma("unroll") for (int k = 0; k < 2; ++k) dst[m][k] = *(const PG8_LAS bf16x8*)(lds + PG8_SA(b, h) + aoff + m * 2048 + k * 1024); } while (0)
; #define PG8_LDB(dst, b, h) do { _Pragma("unroll") for (int n = 0; n < 2; ++n) _Pragma("unroll") for (int k = 0; k < 2; ++k) dst[n][k] = *(const PG8_LAS bf16x8*)(lds + PG8_SB(b, h) + boff + n * 2048 + k * 1024); } while (0)
; #define PG8_WAIT_V(n) asm volatile("s_waitcnt vmcnt(" #n ")" ::: "memory")
; #define PG8_WAIT_L(n) asm volatile("s_waitcnt lgkmcnt(" #n ")" ::: "memory")
; #define PG8_BAR __builtin_amdgcn_s_barrier()
; #define PG8_SCHED __builtin_amdgcn_sched_barrier(0)
; #define PG8_STAGE(bufoff, gbase, voff) do { const char* _gb = (const char*)(gbase); asm volatile("" : "+s"(_gb)); _Pragma("unroll") for (int _i = 0; _i < 2; ++_i) { asm volatile("" : "+v"((voff)[_i])); \
;         __builtin_amdgcn_global_load_lds((const unsigned*)(_gb + (voff)[_i]), (PG8_LAS unsigned*)(lds + (bufoff) + ldsw + _i * 8192), 16, 0, 0); } } while (0)
; #define PG8_LDA(dst, b, h) do { _Pragma("unroll") for (int m = 0; m < 4; ++m) _Pragma("unroll") for (int k = 0; k < 2; ++k) dst[m][k] = *(const PG8_LAS bf16x8*)(lds + PG8_SA(b, h) + aoff + m * 2048 + k * 1024); } while (0)
; #define PG8_WAIT_V(n) asm volatile("s_waitcnt vmcnt(" #n ")" ::: "memory")
; template <class Epi, class Sched, bool ALIGN_EPI = false, bool SP2 = false>
; __device__ __forceinline__ void gemm_phase(PG8_LAS unsigned char* lds, const Gemm g, const Sched& S, const Epi& E) {
;     ...
;             PG8_LDB(B0, 1, 0); PG8_LDB(B1, 1, 1); PG8_SCHED; PG8_LDA(At, 1, 0); PG8_STAGE(PG8_SA(0, 1), a2 + hstep, voffA);
;             PG8_WAIT_V(8); PG8_WAIT_L(0); PG8_BAR; PG8_MMA2(0); PG8_BAR; PG8_SCHED;
;             PG8_LDA(At, 1, 1); PG8_STAGE(PG8_SB(1, 0), b3, voffB); PG8_STAGE(PG8_SB(1, 1), b3 + hstep, voffB); PG8_STAGE(PG8_SA(1, 0), a3, voffA);
;             PG8_WAIT_V(8); PG8_WAIT_L(0); PG8_BAR; PG8_MMA2(1); PG8_BAR; PG8_SCHED;
	s_add_i32 s84, 0, 0x18000
	s_add_i32 s85, 0, 0x1c000
	ds_read_b128 v[58:61], v241
	ds_read_b128 v[62:65], v241 offset:1024
	ds_read_b128 v[138:141], v241 offset:2048
	ds_read_b128 v[142:145], v241 offset:3072
	ds_read_b128 v[164:167], v242
	ds_read_b128 v[168:171], v242 offset:1024
	ds_read_b128 v[172:175], v242 offset:2048
	ds_read_b128 v[176:179], v242 offset:3072
	s_add_u32 s12, s18, 0x100000
	s_addc_u32 s13, s19, 0
	s_mov_b32 m0, s47
	ds_read_b128 v[180:183], v219 offset:32768
	ds_read_b128 v[184:187], v219 offset:33792
	ds_read_b128 v[188:191], v219 offset:34816
	ds_read_b128 v[192:195], v219 offset:35840
	ds_read_b128 v[222:225], v219 offset:36864
	ds_read_b128 v[226:229], v219 offset:37888
	ds_read_b128 v[230:233], v219 offset:38912
	ds_read_b128 v[234:237], v219 offset:39936
	s_nop 0
	global_load_lds_dwordx4 v1, s[12:13]
	s_mov_b32 m0, s87
	s_nop 0
	global_load_lds_dwordx4 v199, s[12:13]
	s_waitcnt vmcnt(8)
	s_waitcnt lgkmcnt(0)
	s_setprio 1
	s_waitcnt lgkmcnt(0)
	s_barrier
	v_mfma_f32_16x16x32_bf16 v[118:121], v[58:61], v[180:183], v[118:121]
	v_mfma_f32_16x16x32_bf16 v[114:117], v[138:141], v[180:183], v[114:117]
	v_mfma_f32_16x16x32_bf16 v[106:109], v[58:61], v[188:191], v[106:109]
	v_mfma_f32_16x16x32_bf16 v[86:89], v[138:141], v[188:191], v[86:89]
	v_mfma_f32_16x16x32_bf16 v[134:137], v[58:61], v[222:225], v[134:137]
	v_mfma_f32_16x16x32_bf16 v[90:93], v[138:141], v[222:225], v[90:93]
	v_mfma_f32_16x16x32_bf16 v[130:133], v[58:61], v[230:233], v[130:133]
	v_mfma_f32_16x16x32_bf16 v[110:113], v[138:141], v[230:233], v[110:113]
	v_mfma_f32_16x16x32_bf16 v[94:97], v[164:167], v[180:183], v[94:97]
	v_mfma_f32_16x16x32_bf16 v[82:85], v[172:175], v[180:183], v[82:85]
	v_mfma_f32_16x16x32_bf16 v[78:81], v[164:167], v[188:191], v[78:81]
	v_mfma_f32_16x16x32_bf16 v[74:77], v[172:175], v[188:191], v[74:77]
	v_mfma_f32_16x16x32_bf16 v[126:129], v[164:167], v[222:225], v[126:129]
	v_mfma_f32_16x16x32_bf16 v[98:101], v[172:175], v[222:225], v[98:101]
	v_mfma_f32_16x16x32_bf16 v[122:125], v[164:167], v[230:233], v[122:125]
	v_mfma_f32_16x16x32_bf16 v[102:105], v[172:175], v[230:233], v[102:105]
	v_mfma_f32_16x16x32_bf16 v[118:121], v[62:65], v[184:187], v[118:121]
	v_mfma_f32_16x16x32_bf16 v[114:117], v[142:145], v[184:187], v[114:117]
	v_mfma_f32_16x16x32_bf16 v[106:109], v[62:65], v[192:195], v[106:109]
	v_mfma_f32_16x16x32_bf16 v[86:89], v[142:145], v[192:195], v[86:89]
	v_mfma_f32_16x16x32_bf16 v[134:137], v[62:65], v[226:229], v[134:137]
	v_mfma_f32_16x16x32_bf16 v[90:93], v[142:145], v[226:229], v[90:93]
	v_mfma_f32_16x16x32_bf16 v[130:133], v[62:65], v[234:237], v[130:133]
	v_mfma_f32_16x16x32_bf16 v[110:113], v[142:145], v[234:237], v[110:113]
	v_mfma_f32_16x16x32_bf16 v[94:97], v[168:171], v[184:187], v[94:97]
	v_mfma_f32_16x16x32_bf16 v[82:85], v[176:179], v[184:187], v[82:85]
	v_mfma_f32_16x16x32_bf16 v[78:81], v[168:171], v[192:195], v[78:81]
	v_mfma_f32_16x16x32_bf16 v[74:77], v[176:179], v[192:195], v[74:77]
	v_mfma_f32_16x16x32_bf16 v[126:129], v[168:171], v[226:229], v[126:129]
	v_mfma_f32_16x16x32_bf16 v[98:101], v[176:179], v[226:229], v[98:101]
	v_mfma_f32_16x16x32_bf16 v[122:125], v[168:171], v[234:237], v[122:125]
	v_mfma_f32_16x16x32_bf16 v[102:105], v[176:179], v[234:237], v[102:105]
	s_setprio 0
	s_barrier
	s_add_u32 s12, s16, 0x80
	s_addc_u32 s13, s17, 0
	s_add_i32 s18, s84, s25
	s_mov_b32 m0, s18
	ds_read_b128 v[180:183], v219 offset:49152
	ds_read_b128 v[184:187], v219 offset:50176
	ds_read_b128 v[188:191], v219 offset:51200
	ds_read_b128 v[192:195], v219 offset:52224
	ds_read_b128 v[222:225], v219 offset:53248
	ds_read_b128 v[226:229], v219 offset:54272
	ds_read_b128 v[230:233], v219 offset:55296
	ds_read_b128 v[234:237], v219 offset:56320
	s_nop 0
	global_load_lds_dwordx4 v198, s[12:13]
	s_add_i32 m0, s18, 0x2000
	s_nop 0
	global_load_lds_dwordx4 v200, s[12:13]
	s_add_u32 s12, s16, 0x100080
	s_addc_u32 s13, s17, 0
	s_add_i32 s16, s85, s25
	s_mov_b32 m0, s16
	s_nop 0
	global_load_lds_dwordx4 v198, s[12:13]
	s_add_i32 m0, s16, 0x2000
	s_nop 0
	global_load_lds_dwordx4 v200, s[12:13]
	s_mov_b32 m0, s71
	s_nop 0
	global_load_lds_dwordx4 v1, s[2:3]
	s_mov_b32 m0, s72
	s_nop 0
	global_load_lds_dwordx4 v199, s[2:3]
	s_waitcnt vmcnt(8)
	s_waitcnt lgkmcnt(0)
	s_setprio 1
	s_waitcnt lgkmcnt(0)
	s_barrier
	v_mfma_f32_16x16x32_bf16 v[6:9], v[58:61], v[230:233], v[6:9]
	v_mfma_f32_16x16x32_bf16 v[34:37], v[58:61], v[180:183], v[34:37]
	v_mfma_f32_16x16x32_bf16 v[26:29], v[58:61], v[188:191], v[26:29]
	v_mfma_f32_16x16x32_bf16 v[70:73], v[58:61], v[222:225], v[70:73]
	v_mfma_f32_16x16x32_bf16 v[58:61], v[62:65], v[234:237], v[6:9]
	v_mfma_f32_16x16x32_bf16 v[6:9], v[138:141], v[230:233], v[50:53]
	v_mfma_f32_16x16x32_bf16 v[50:53], v[142:145], v[234:237], v[6:9]
	v_mfma_f32_16x16x32_bf16 v[6:9], v[164:167], v[180:183], v[18:21]
	v_mfma_f32_16x16x32_bf16 v[18:21], v[168:171], v[184:187], v[6:9]
	v_mfma_f32_16x16x32_bf16 v[6:9], v[172:175], v[180:183], v[14:17]
	v_mfma_f32_16x16x32_bf16 v[14:17], v[176:179], v[184:187], v[6:9]
	v_mfma_f32_16x16x32_bf16 v[6:9], v[164:167], v[188:191], v[10:13]
	v_mfma_f32_16x16x32_bf16 v[10:13], v[168:171], v[192:195], v[6:9]
	v_mfma_f32_16x16x32_bf16 v[6:9], v[164:167], v[222:225], v[54:57]
	v_mfma_f32_16x16x32_bf16 v[54:57], v[168:171], v[226:229], v[6:9]
	v_mfma_f32_16x16x32_bf16 v[6:9], v[172:175], v[222:225], v[46:49]
	v_mfma_f32_16x16x32_bf16 v[46:49], v[176:179], v[226:229], v[6:9]
	v_mfma_f32_16x16x32_bf16 v[6:9], v[164:167], v[230:233], v[42:45]
	v_mfma_f32_16x16x32_bf16 v[30:33], v[138:141], v[180:183], v[30:33]
	v_mfma_f32_16x16x32_bf16 v[22:25], v[138:141], v[188:191], v[22:25]
	v_mfma_f32_16x16x32_bf16 v[66:69], v[138:141], v[222:225], v[66:69]
	v_mfma_f32_16x16x32_bf16 v[2:5], v[172:175], v[188:191], v[2:5]
	v_mfma_f32_16x16x32_bf16 v[42:45], v[168:171], v[234:237], v[6:9]
	v_mfma_f32_16x16x32_bf16 v[6:9], v[172:175], v[230:233], v[38:41]
	v_mfma_f32_16x16x32_bf16 v[34:37], v[62:65], v[184:187], v[34:37]
	v_mfma_f32_16x16x32_bf16 v[30:33], v[142:145], v[184:187], v[30:33]
	v_mfma_f32_16x16x32_bf16 v[26:29], v[62:65], v[192:195], v[26:29]
	v_mfma_f32_16x16x32_bf16 v[22:25], v[142:145], v[192:195], v[22:25]
	v_mfma_f32_16x16x32_bf16 v[70:73], v[62:65], v[226:229], v[70:73]
	v_mfma_f32_16x16x32_bf16 v[66:69], v[142:145], v[226:229], v[66:69]
	v_mfma_f32_16x16x32_bf16 v[2:5], v[176:179], v[192:195], v[2:5]
	v_mfma_f32_16x16x32_bf16 v[38:41], v[176:179], v[234:237], v[6:9]
	s_setprio 0
	s_barrier
	s_add_i32 s83, s83, 2
	s_add_u32 s62, s62, 0x100
	s_addc_u32 s63, s63, 0
	s_cmp_gt_u32 s83, 61
	s_mov_b64 s[12:13], s[14:15]
	s_cbranch_scc0 .LBB0_933
	s_and_b64 vcc, exec, s[38:39]
	s_cbranch_vccz .LBB0_936
	s_barrier

;     __device__ bool next(int i, Unit& u) const { if (i > 1) return false; const int xcd = c & 7, idx = c >> 3; u.pm = 16 * i + 4 * (xcd >> 1) + (idx & 3); u.pn = 8 * (xcd & 1) + (idx >> 2); return true; }
; #define PG8_STAGE(bufoff, gbase, voff) do { const char* _gb = (const char*)(gbase); asm volatile("" : "+s"(_gb)); _Pragma("unroll") for (int _i = 0; _i < 2; ++_i) { asm volatile("" : "+v"((voff)[_i])); \
;         __builtin_amdgcn_global_load_lds((const unsigned*)(_gb + (voff)[_i]), (PG8_LAS unsigned*)(lds + (bufoff) + ldsw + _i * 8192), 16, 0, 0); } } while (0)
; #define PG8_LDA(dst, b, h) do { _Pragma("unroll") for (int m = 0; m < 4; ++m) _Pragma("unroll") for (int k = 0; k < 2; ++k) dst[m][k] = *(const PG8_LAS bf16x8*)(lds + PG8_SA(b, h) + aoff + m * 2048 + k * 1024); } while (0)
; #define PG8_LDB(dst, b, h) do { _Pragma("unroll") for (int n = 0; n < 2; ++n) _Pragma("unroll") for (int k = 0; k < 2; ++k) dst[n][k] = *(const PG8_LAS bf16x8*)(lds + PG8_SB(b, h) + boff + n * 2048 + k * 1024); } while (0)
; #define PG8_SCHED __builtin_amdgcn_sched_barrier(0)
; template <class Epi, class Sched, bool ALIGN_EPI = false, bool SP2 = false>
; __device__ __forceinline__ void gemm_phase(PG8_LAS unsigned char* lds, const Gemm g, const Sched& S, const Epi& E) {
;     ...
;         const bool has_next = S.next(ui + 1, nxt);
;         const char* nA = has_next ? (const char*)g.A + (size_t)nxt.pm * tstep : cA; const char* nB = has_next ? (const char*)g.Bt + (size_t)nxt.pn * tstep : cB;
;         for (int t = 0; t < nt; t += 2) {
;             const bool last = (t == nt - 2);
;             const char* a1 = cA + (size_t)(t + 1) * kstep;
;             const char* a2 = last ? nA : cA + (size_t)(t + 2) * kstep; const char* b2 = last ? nB : cB + (size_t)(t + 2) * kstep;
;             const char* a3 = a2 + kstep; const char* b3 = b2 + kstep;
;             if (last && has_next) S.a_ready(nxt);
;             if constexpr (SP2) {
;             PG8_LDB(B0, 0, 0); PG8_LDB(B1, 0, 1); PG8_SCHED; PG8_LDA(At, 0, 0); PG8_STAGE(PG8_SA(1, 1), a1 + hstep, voffA);
;     ...
; #pragma unroll
;         for (int a = 0; a < 2; ++a)
; #pragma unroll
;             for (int b = 0; b < 2; ++b)
; #pragma unroll
;                 for (int m = 0; m < 4; ++m)
; #pragma unroll
;                     for (int n = 0; n < 2; ++n) acc[a][b][m][n] = (f32x4){0.f, 0.f, 0.f, 0.f};
;         cur = nxt; cA = nA; cB = nB; ++ui;
.LBB0_1216:
	s_mov_b32 s14, s55
	s_or_b32 s55, s28, s40
	s_mul_i32 s4, s55, 0x600000
	s_mov_b64 s[6:7], s[10:11]
	s_add_u32 s10, s33, s4
	s_addc_u32 s11, s38, 0
	s_and_b64 s[4:5], s[26:27], exec
	s_cselect_b32 s56, s11, s7
	s_cselect_b32 s57, s10, s6
	s_mov_b32 s58, -2
	s_mov_b64 s[4:5], s[20:21]
	v_mov_b32_e32 v0, 0
	v_mov_b32_e32 v1, v179
	v_mov_b32_e32 v2, v179
	v_mov_b32_e32 v3, v179
	v_mov_b32_e32 v4, 0
	v_mov_b32_e32 v5, v179
	v_mov_b32_e32 v6, v179
	v_mov_b32_e32 v7, v179
	v_mov_b32_e32 v16, 0
	v_mov_b32_e32 v17, v179
	v_mov_b32_e32 v18, v179
	v_mov_b32_e32 v19, v179
	v_mov_b32_e32 v20, 0
	v_mov_b32_e32 v21, v179
	v_mov_b32_e32 v22, v179
	v_mov_b32_e32 v23, v179
	v_mov_b32_e32 v32, 0
	v_mov_b32_e32 v33, v179
	v_mov_b32_e32 v34, v179
	v_mov_b32_e32 v35, v179
	v_mov_b32_e32 v36, 0
	v_mov_b32_e32 v37, v179
	v_mov_b32_e32 v38, v179
	v_mov_b32_e32 v39, v179
	v_mov_b32_e32 v48, 0
	v_mov_b32_e32 v49, v179
	v_mov_b32_e32 v50, v179
	v_mov_b32_e32 v51, v179
	v_mov_b32_e32 v52, 0
	v_mov_b32_e32 v53, v179
	v_mov_b32_e32 v54, v179
	v_mov_b32_e32 v55, v179
	v_mov_b32_e32 v8, 0
	v_mov_b32_e32 v9, v179
	v_mov_b32_e32 v10, v179
	v_mov_b32_e32 v11, v179
	v_mov_b32_e32 v12, 0
	v_mov_b32_e32 v13, v179
	v_mov_b32_e32 v14, v179
	v_mov_b32_e32 v15, v179
	v_mov_b32_e32 v24, 0
	v_mov_b32_e32 v25, v179
	v_mov_b32_e32 v26, v179
	v_mov_b32_e32 v27, v179
	v_mov_b32_e32 v28, 0
	v_mov_b32_e32 v29, v179
	v_mov_b32_e32 v30, v179
	v_mov_b32_e32 v31, v179
	v_mov_b32_e32 v40, 0
	v_mov_b32_e32 v41, v179
	v_mov_b32_e32 v42, v179
	v_mov_b32_e32 v43, v179
	v_mov_b32_e32 v44, 0
	v_mov_b32_e32 v45, v179
	v_mov_b32_e32 v46, v179
	v_mov_b32_e32 v47, v179
	v_mov_b32_e32 v56, 0
	v_mov_b32_e32 v57, v179
	v_mov_b32_e32 v58, v179
	v_mov_b32_e32 v59, v179
	v_mov_b32_e32 v60, 0
	v_mov_b32_e32 v61, v179
	v_mov_b32_e32 v62, v179
	v_mov_b32_e32 v63, v179
	v_mov_b32_e32 v64, 0
	v_mov_b32_e32 v65, v179
	v_mov_b32_e32 v66, v179
	v_mov_b32_e32 v67, v179
	v_mov_b32_e32 v68, 0
	v_mov_b32_e32 v69, v179
	v_mov_b32_e32 v70, v179
	v_mov_b32_e32 v71, v179
	v_mov_b32_e32 v80, 0
	v_mov_b32_e32 v81, v179
	v_mov_b32_e32 v82, v179
	v_mov_b32_e32 v83, v179
	v_mov_b32_e32 v84, 0
	v_mov_b32_e32 v85, v179
	v_mov_b32_e32 v86, v179
	v_mov_b32_e32 v87, v179
	v_mov_b32_e32 v96, 0
	v_mov_b32_e32 v97, v179
	v_mov_b32_e32 v98, v179
	v_mov_b32_e32 v99, v179
	v_mov_b32_e32 v100, 0
	v_mov_b32_e32 v101, v179
	v_mov_b32_e32 v102, v179
	v_mov_b32_e32 v103, v179
	v_mov_b32_e32 v112, 0
	v_mov_b32_e32 v113, v179
	v_mov_b32_e32 v114, v179
	v_mov_b32_e32 v115, v179
	v_mov_b32_e32 v116, 0
	v_mov_b32_e32 v117, v179
	v_mov_b32_e32 v118, v179
	v_mov_b32_e32 v119, v179
	v_mov_b32_e32 v72, 0
	v_mov_b32_e32 v73, v179
	v_mov_b32_e32 v74, v179
	v_mov_b32_e32 v75, v179
	v_mov_b32_e32 v76, 0
	v_mov_b32_e32 v77, v179
	v_mov_b32_e32 v78, v179
	v_mov_b32_e32 v79, v179
	v_mov_b32_e32 v88, 0
	v_mov_b32_e32 v89, v179
	v_mov_b32_e32 v90, v179
	v_mov_b32_e32 v91, v179
	v_mov_b32_e32 v92, 0
	v_mov_b32_e32 v93, v179
	v_mov_b32_e32 v94, v179
	v_mov_b32_e32 v95, v179
	v_mov_b32_e32 v104, 0
	v_mov_b32_e32 v105, v179
	v_mov_b32_e32 v106, v179
	v_mov_b32_e32 v107, v179
	v_mov_b32_e32 v108, 0
	v_mov_b32_e32 v109, v179
	v_mov_b32_e32 v110, v179
	v_mov_b32_e32 v111, v179
	v_mov_b32_e32 v120, 0
	v_mov_b32_e32 v121, v179
	v_mov_b32_e32 v122, v179
	v_mov_b32_e32 v123, v179
	v_mov_b32_e32 v124, 0
	v_mov_b32_e32 v125, v179
	v_mov_b32_e32 v126, v179
	v_mov_b32_e32 v127, v179
	v_add_u32_e32 v239, 0x18000, v174
	v_add_u32_e32 v240, 0x1c000, v174
.LBB0_1217:
	ds_read_b128 v[128:131], v175
	ds_read_b128 v[132:135], v175 offset:1024
	ds_read_b128 v[136:139], v175 offset:2048
	ds_read_b128 v[140:143], v175 offset:3072
	ds_read_b128 v[152:155], v176
	ds_read_b128 v[156:159], v176 offset:1024
	ds_read_b128 v[160:163], v176 offset:2048
	ds_read_b128 v[184:187], v176 offset:3072
	s_add_u32 s28, s6, 0x100
	s_addc_u32 s29, s7, 0
	s_cmpk_eq_i32 s58, 0xbc
	s_cselect_b32 s36, s57, s28
	s_cselect_b32 s37, s56, s29
	s_cselect_b32 s34, s8, s4
	s_cselect_b32 s35, s9, s5
	s_add_u32 s30, s36, 0x80
	s_addc_u32 s31, s37, 0
	s_add_u32 s6, s6, 0x300080
	s_addc_u32 s7, s7, 0
	s_add_i32 m0, s41, 0xc000
	ds_read_b128 v[188:191], v177
	ds_read_b128 v[192:195], v177 offset:1024
	ds_read_b128 v[196:199], v177 offset:2048
	ds_read_b128 v[200:203], v177 offset:3072
	ds_read_b128 v[204:207], v177 offset:4096
	ds_read_b128 v[208:211], v177 offset:5120
	ds_read_b128 v[212:215], v177 offset:6144
	ds_read_b128 v[216:219], v177 offset:7168
	s_nop 0
	global_load_lds_dwordx4 v167, s[6:7]
	s_add_i32 m0, s41, 0xe000
	s_nop 0
	global_load_lds_dwordx4 v171, s[6:7]
	s_waitcnt vmcnt(8)
	s_waitcnt lgkmcnt(0)
	s_setprio 1
	s_waitcnt lgkmcnt(0)
	s_barrier
; #define PG8_STAGE(bufoff, gbase, voff) do { const char* _gb = (const char*)(gbase); asm volatile("" : "+s"(_gb)); _Pragma("unroll") for (int _i = 0; _i < 2; ++_i) { asm volatile("" : "+v"((voff)[_i])); \
;         __builtin_amdgcn_global_load_lds((const unsigned*)(_gb + (voff)[_i]), (PG8_LAS unsigned*)(lds + (bufoff) + ldsw + _i * 8192), 16, 0, 0); } } while (0)
; #define PG8_LDA(dst, b, h) do { _Pragma("unroll") for (int m = 0; m < 4; ++m) _Pragma("unroll") for (int k = 0; k < 2; ++k) dst[m][k] = *(const PG8_LAS bf16x8*)(lds + PG8_SA(b, h) + aoff + m * 2048 + k * 1024); } while (0)
; #define PG8_LDB(dst, b, h) do { _Pragma("unroll") for (int n = 0; n < 2; ++n) _Pragma("unroll") for (int k = 0; k < 2; ++k) dst[n][k] = *(const PG8_LAS bf16x8*)(lds + PG8_SB(b, h) + boff + n * 2048 + k * 1024); } while (0)
; #define PG8_WAIT_V(n) asm volatile("s_waitcnt vmcnt(" #n ")" ::: "memory")
; #define PG8_WAIT_L(n) asm volatile("s_waitcnt lgkmcnt(" #n ")" ::: "memory")
; #define PG8_BAR __builtin_amdgcn_s_barrier()
; #define PG8_SCHED __builtin_amdgcn_sched_barrier(0)
; #define PG8_STAGE(bufoff, gbase, voff) do { const char* _gb = (const char*)(gbase); asm volatile("" : "+s"(_gb)); _Pragma("unroll") for (int _i = 0; _i < 2; ++_i) { asm volatile("" : "+v"((voff)[_i])); \
;         __builtin_amdgcn_global_load_lds((const unsigned*)(_gb + (voff)[_i]), (PG8_LAS unsigned*)(lds + (bufoff) + ldsw + _i * 8192), 16, 0, 0); } } while (0)
; #define PG8_LDA(dst, b, h) do { _Pragma("unroll") for (int m = 0; m < 4; ++m) _Pragma("unroll") for (int k = 0; k < 2; ++k) dst[m][k] = *(const PG8_LAS bf16x8*)(lds + PG8_SA(b, h) + aoff + m * 2048 + k * 1024); } while (0)
; #define PG8_WAIT_V(n) asm volatile("s_waitcnt vmcnt(" #n ")" ::: "memory")
; template <class Epi, class Sched, bool ALIGN_EPI = false, bool SP2 = false>
; __device__ __forceinline__ void gemm_phase(PG8_LAS unsigned char* lds, const Gemm g, const Sched& S, const Epi& E) {
;     ...
;             PG8_LDB(B0, 0, 0); PG8_LDB(B1, 0, 1); PG8_SCHED; PG8_LDA(At, 0, 0); PG8_STAGE(PG8_SA(1, 1), a1 + hstep, voffA);
;             PG8_WAIT_V(8); PG8_WAIT_L(0); PG8_BAR; PG8_MMA2(0); PG8_BAR; PG8_SCHED;
;             PG8_LDA(At, 0, 1); PG8_STAGE(PG8_SB(0, 0), b2, voffB); PG8_STAGE(PG8_SB(0, 1), b2 + hstep, voffB); PG8_STAGE(PG8_SA(0, 0), a2, voffA);
;             PG8_WAIT_V(8); PG8_WAIT_L(0); PG8_BAR; PG8_MMA2(1); PG8_BAR; PG8_SCHED;
	v_mfma_f32_16x16x32_bf16 v[124:127], v[128:131], v[188:191], v[124:127]
	v_mfma_f32_16x16x32_bf16 v[120:123], v[136:139], v[188:191], v[120:123]
	v_mfma_f32_16x16x32_bf16 v[108:111], v[128:131], v[196:199], v[108:111]
	v_mfma_f32_16x16x32_bf16 v[104:107], v[136:139], v[196:199], v[104:107]
	v_mfma_f32_16x16x32_bf16 v[92:95], v[128:131], v[204:207], v[92:95]
	v_mfma_f32_16x16x32_bf16 v[88:91], v[136:139], v[204:207], v[88:91]
	v_mfma_f32_16x16x32_bf16 v[76:79], v[128:131], v[212:215], v[76:79]
	v_mfma_f32_16x16x32_bf16 v[72:75], v[136:139], v[212:215], v[72:75]
	v_mfma_f32_16x16x32_bf16 v[116:119], v[152:155], v[188:191], v[116:119]
	v_mfma_f32_16x16x32_bf16 v[112:115], v[160:163], v[188:191], v[112:115]
	v_mfma_f32_16x16x32_bf16 v[100:103], v[152:155], v[196:199], v[100:103]
	v_mfma_f32_16x16x32_bf16 v[96:99], v[160:163], v[196:199], v[96:99]
	v_mfma_f32_16x16x32_bf16 v[84:87], v[152:155], v[204:207], v[84:87]
	v_mfma_f32_16x16x32_bf16 v[80:83], v[160:163], v[204:207], v[80:83]
	v_mfma_f32_16x16x32_bf16 v[68:71], v[152:155], v[212:215], v[68:71]
	v_mfma_f32_16x16x32_bf16 v[64:67], v[160:163], v[212:215], v[64:67]
	v_mfma_f32_16x16x32_bf16 v[124:127], v[132:135], v[192:195], v[124:127]
	v_mfma_f32_16x16x32_bf16 v[120:123], v[140:143], v[192:195], v[120:123]
	v_mfma_f32_16x16x32_bf16 v[108:111], v[132:135], v[200:203], v[108:111]
	v_mfma_f32_16x16x32_bf16 v[104:107], v[140:143], v[200:203], v[104:107]
	v_mfma_f32_16x16x32_bf16 v[92:95], v[132:135], v[208:211], v[92:95]
	v_mfma_f32_16x16x32_bf16 v[88:91], v[140:143], v[208:211], v[88:91]
	v_mfma_f32_16x16x32_bf16 v[76:79], v[132:135], v[216:219], v[76:79]
	v_mfma_f32_16x16x32_bf16 v[72:75], v[140:143], v[216:219], v[72:75]
	v_mfma_f32_16x16x32_bf16 v[116:119], v[156:159], v[192:195], v[116:119]
	v_mfma_f32_16x16x32_bf16 v[112:115], v[184:187], v[192:195], v[112:115]
	v_mfma_f32_16x16x32_bf16 v[100:103], v[156:159], v[200:203], v[100:103]
	v_mfma_f32_16x16x32_bf16 v[96:99], v[184:187], v[200:203], v[96:99]
	v_mfma_f32_16x16x32_bf16 v[84:87], v[156:159], v[208:211], v[84:87]
	v_mfma_f32_16x16x32_bf16 v[80:83], v[184:187], v[208:211], v[80:83]
	v_mfma_f32_16x16x32_bf16 v[68:71], v[156:159], v[216:219], v[68:71]
	v_mfma_f32_16x16x32_bf16 v[64:67], v[184:187], v[216:219], v[64:67]
	s_setprio 0
	s_barrier
	s_add_i32 s59, s49, s39
	s_mov_b64 s[6:7], s[34:35]
	s_mov_b32 m0, s59
	ds_read_b128 v[188:191], v177 offset:16384
	ds_read_b128 v[192:195], v177 offset:17408
	ds_read_b128 v[196:199], v177 offset:18432
	ds_read_b128 v[200:203], v177 offset:19456
	ds_read_b128 v[204:207], v177 offset:20480
	ds_read_b128 v[208:211], v177 offset:21504
	ds_read_b128 v[212:215], v177 offset:22528
	ds_read_b128 v[216:219], v177 offset:23552
	s_nop 0
	global_load_lds_dwordx4 v169, s[6:7]
	s_add_i32 m0, s59, 0x2000
	s_nop 0
	global_load_lds_dwordx4 v172, s[6:7]
	s_add_u32 s6, s34, 0x300000
	s_addc_u32 s7, s35, 0
	s_add_i32 s59, s50, s39
	s_mov_b32 m0, s59
	s_nop 0
	global_load_lds_dwordx4 v169, s[6:7]
	s_add_i32 m0, s59, 0x2000
	s_nop 0
	global_load_lds_dwordx4 v172, s[6:7]
	s_mov_b64 s[6:7], s[36:37]
	s_mov_b32 m0, s41
	s_nop 0
	global_load_lds_dwordx4 v167, s[6:7]
	s_mov_b32 m0, s42
	s_nop 0
	global_load_lds_dwordx4 v171, s[6:7]
	s_waitcnt vmcnt(8)
	s_waitcnt lgkmcnt(0)
	s_setprio 1
	s_waitcnt lgkmcnt(0)
	s_barrier
	v_mfma_f32_16x16x32_bf16 v[60:63], v[128:131], v[188:191], v[60:63]
	v_mfma_f32_16x16x32_bf16 v[56:59], v[136:139], v[188:191], v[56:59]
	v_mfma_f32_16x16x32_bf16 v[44:47], v[128:131], v[196:199], v[44:47]
	v_mfma_f32_16x16x32_bf16 v[40:43], v[136:139], v[196:199], v[40:43]
	v_mfma_f32_16x16x32_bf16 v[28:31], v[128:131], v[204:207], v[28:31]
	v_mfma_f32_16x16x32_bf16 v[24:27], v[136:139], v[204:207], v[24:27]
	v_mfma_f32_16x16x32_bf16 v[12:15], v[128:131], v[212:215], v[12:15]
	v_mfma_f32_16x16x32_bf16 v[8:11], v[136:139], v[212:215], v[8:11]
	v_mfma_f32_16x16x32_bf16 v[52:55], v[152:155], v[188:191], v[52:55]
	v_mfma_f32_16x16x32_bf16 v[48:51], v[160:163], v[188:191], v[48:51]
	v_mfma_f32_16x16x32_bf16 v[36:39], v[152:155], v[196:199], v[36:39]
	v_mfma_f32_16x16x32_bf16 v[32:35], v[160:163], v[196:199], v[32:35]
	v_mfma_f32_16x16x32_bf16 v[20:23], v[152:155], v[204:207], v[20:23]
	v_mfma_f32_16x16x32_bf16 v[16:19], v[160:163], v[204:207], v[16:19]
	v_mfma_f32_16x16x32_bf16 v[4:7], v[152:155], v[212:215], v[4:7]
	v_mfma_f32_16x16x32_bf16 v[0:3], v[160:163], v[212:215], v[0:3]
	v_mfma_f32_16x16x32_bf16 v[60:63], v[132:135], v[192:195], v[60:63]
	v_mfma_f32_16x16x32_bf16 v[56:59], v[140:143], v[192:195], v[56:59]
	v_mfma_f32_16x16x32_bf16 v[44:47], v[132:135], v[200:203], v[44:47]
	v_mfma_f32_16x16x32_bf16 v[40:43], v[140:143], v[200:203], v[40:43]
	v_mfma_f32_16x16x32_bf16 v[28:31], v[132:135], v[208:211], v[28:31]
	v_mfma_f32_16x16x32_bf16 v[24:27], v[140:143], v[208:211], v[24:27]
	v_mfma_f32_16x16x32_bf16 v[12:15], v[132:135], v[216:219], v[12:15]
	v_mfma_f32_16x16x32_bf16 v[8:11], v[140:143], v[216:219], v[8:11]
	v_mfma_f32_16x16x32_bf16 v[52:55], v[156:159], v[192:195], v[52:55]
	v_mfma_f32_16x16x32_bf16 v[48:51], v[184:187], v[192:195], v[48:51]
	v_mfma_f32_16x16x32_bf16 v[36:39], v[156:159], v[200:203], v[36:39]
	v_mfma_f32_16x16x32_bf16 v[32:35], v[184:187], v[200:203], v[32:35]
	v_mfma_f32_16x16x32_bf16 v[20:23], v[156:159], v[208:211], v[20:23]
	v_mfma_f32_16x16x32_bf16 v[16:19], v[184:187], v[208:211], v[16:19]
	v_mfma_f32_16x16x32_bf16 v[4:7], v[156:159], v[216:219], v[4:7]
	v_mfma_f32_16x16x32_bf16 v[0:3], v[184:187], v[216:219], v[0:3]
	s_setprio 0
	s_barrier
; #define PG8_STAGE(bufoff, gbase, voff) do { const char* _gb = (const char*)(gbase); asm volatile("" : "+s"(_gb)); _Pragma("unroll") for (int _i = 0; _i < 2; ++_i) { asm volatile("" : "+v"((voff)[_i])); \
;         __builtin_amdgcn_global_load_lds((const unsigned*)(_gb + (voff)[_i]), (PG8_LAS unsigned*)(lds + (bufoff) + ldsw + _i * 8192), 16, 0, 0); } } while (0)
; #define PG8_LDA(dst, b, h) do { _Pragma("unroll") for (int m = 0; m < 4; ++m) _Pragma("unroll") for (int k = 0; k < 2; ++k) dst[m][k] = *(const PG8_LAS bf16x8*)(lds + PG8_SA(b, h) + aoff + m * 2048 + k * 1024); } while (0)
; #define PG8_LDB(dst, b, h) do { _Pragma("unroll") for (int n = 0; n < 2; ++n) _Pragma("unroll") for (int k = 0; k < 2; ++k) dst[n][k] = *(const PG8_LAS bf16x8*)(lds + PG8_SB(b, h) + boff + n * 2048 + k * 1024); } while (0)
; #define PG8_WAIT_V(n) asm volatile("s_waitcnt vmcnt(" #n ")" ::: "memory")
; #define PG8_WAIT_L(n) asm volatile("s_waitcnt lgkmcnt(" #n ")" ::: "memory")
; #define PG8_BAR __builtin_amdgcn_s_barrier()
; #define PG8_SCHED __builtin_amdgcn_sched_barrier(0)
; #define PG8_STAGE(bufoff, gbase, voff) do { const char* _gb = (const char*)(gbase); asm volatile("" : "+s"(_gb)); _Pragma("unroll") for (int _i = 0; _i < 2; ++_i) { asm volatile("" : "+v"((voff)[_i])); \
;         __builtin_amdgcn_global_load_lds((const unsigned*)(_gb + (voff)[_i]), (PG8_LAS unsigned*)(lds + (bufoff) + ldsw + _i * 8192), 16, 0, 0); } } while (0)
; #define PG8_LDA(dst, b, h) do { _Pragma("unroll") for (int m = 0; m < 4; ++m) _Pragma("unroll") for (int k = 0; k < 2; ++k) dst[m][k] = *(const PG8_LAS bf16x8*)(lds + PG8_SA(b, h) + aoff + m * 2048 + k * 1024); } while (0)
; #define PG8_WAIT_V(n) asm volatile("s_waitcnt vmcnt(" #n ")" ::: "memory")
; template <class Epi, class Sched, bool ALIGN_EPI = false, bool SP2 = false>
; __device__ __forceinline__ void gemm_phase(PG8_LAS unsigned char* lds, const Gemm g, const Sched& S, const Epi& E) {
;     ...
;             PG8_LDB(B0, 1, 0); PG8_LDB(B1, 1, 1); PG8_SCHED; PG8_LDA(At, 1, 0); PG8_STAGE(PG8_SA(0, 1), a2 + hstep, voffA);
;             PG8_WAIT_V(8); PG8_WAIT_L(0); PG8_BAR; PG8_MMA2(0); PG8_BAR; PG8_SCHED;
;             PG8_LDA(At, 1, 1); PG8_STAGE(PG8_SB(1, 0), b3, voffB); PG8_STAGE(PG8_SB(1, 1), b3 + hstep, voffB); PG8_STAGE(PG8_SA(1, 0), a3, voffA);
;             PG8_WAIT_V(8); PG8_WAIT_L(0); PG8_BAR; PG8_MMA2(1); PG8_BAR; PG8_SCHED;
	s_add_i32 s59, 0, 0x18000
	s_add_i32 s60, 0, 0x1c000
	ds_read_b128 v[128:131], v239
	ds_read_b128 v[132:135], v239 offset:1024
	ds_read_b128 v[136:139], v239 offset:2048
	ds_read_b128 v[140:143], v239 offset:3072
	ds_read_b128 v[152:155], v240
	ds_read_b128 v[156:159], v240 offset:1024
	ds_read_b128 v[160:163], v240 offset:2048
	ds_read_b128 v[184:187], v240 offset:3072
	s_add_u32 s6, s36, 0x300000
	s_addc_u32 s7, s37, 0
	s_mov_b32 m0, s43
	ds_read_b128 v[188:191], v177 offset:32768
	ds_read_b128 v[192:195], v177 offset:33792
	ds_read_b128 v[196:199], v177 offset:34816
	ds_read_b128 v[200:203], v177 offset:35840
	ds_read_b128 v[204:207], v177 offset:36864
	ds_read_b128 v[208:211], v177 offset:37888
	ds_read_b128 v[212:215], v177 offset:38912
	ds_read_b128 v[216:219], v177 offset:39936
	s_nop 0
	global_load_lds_dwordx4 v167, s[6:7]
	s_mov_b32 m0, s44
	s_nop 0
	global_load_lds_dwordx4 v171, s[6:7]
	s_waitcnt vmcnt(8)
	s_waitcnt lgkmcnt(0)
	s_setprio 1
	s_waitcnt lgkmcnt(0)
	s_barrier
	v_mfma_f32_16x16x32_bf16 v[124:127], v[128:131], v[188:191], v[124:127]
	v_mfma_f32_16x16x32_bf16 v[120:123], v[136:139], v[188:191], v[120:123]
	v_mfma_f32_16x16x32_bf16 v[108:111], v[128:131], v[196:199], v[108:111]
	v_mfma_f32_16x16x32_bf16 v[104:107], v[136:139], v[196:199], v[104:107]
	v_mfma_f32_16x16x32_bf16 v[92:95], v[128:131], v[204:207], v[92:95]
	v_mfma_f32_16x16x32_bf16 v[88:91], v[136:139], v[204:207], v[88:91]
	v_mfma_f32_16x16x32_bf16 v[76:79], v[128:131], v[212:215], v[76:79]
	v_mfma_f32_16x16x32_bf16 v[72:75], v[136:139], v[212:215], v[72:75]
	v_mfma_f32_16x16x32_bf16 v[116:119], v[152:155], v[188:191], v[116:119]
	v_mfma_f32_16x16x32_bf16 v[112:115], v[160:163], v[188:191], v[112:115]
	v_mfma_f32_16x16x32_bf16 v[100:103], v[152:155], v[196:199], v[100:103]
	v_mfma_f32_16x16x32_bf16 v[96:99], v[160:163], v[196:199], v[96:99]
	v_mfma_f32_16x16x32_bf16 v[84:87], v[152:155], v[204:207], v[84:87]
	v_mfma_f32_16x16x32_bf16 v[80:83], v[160:163], v[204:207], v[80:83]
	v_mfma_f32_16x16x32_bf16 v[68:71], v[152:155], v[212:215], v[68:71]
	v_mfma_f32_16x16x32_bf16 v[64:67], v[160:163], v[212:215], v[64:67]
	v_mfma_f32_16x16x32_bf16 v[124:127], v[132:135], v[192:195], v[124:127]
	v_mfma_f32_16x16x32_bf16 v[120:123], v[140:143], v[192:195], v[120:123]
	v_mfma_f32_16x16x32_bf16 v[108:111], v[132:135], v[200:203], v[108:111]
	v_mfma_f32_16x16x32_bf16 v[104:107], v[140:143], v[200:203], v[104:107]
	v_mfma_f32_16x16x32_bf16 v[92:95], v[132:135], v[208:211], v[92:95]
	v_mfma_f32_16x16x32_bf16 v[88:91], v[140:143], v[208:211], v[88:91]
	v_mfma_f32_16x16x32_bf16 v[76:79], v[132:135], v[216:219], v[76:79]
	v_mfma_f32_16x16x32_bf16 v[72:75], v[140:143], v[216:219], v[72:75]
	v_mfma_f32_16x16x32_bf16 v[116:119], v[156:159], v[192:195], v[116:119]
	v_mfma_f32_16x16x32_bf16 v[112:115], v[184:187], v[192:195], v[112:115]
	v_mfma_f32_16x16x32_bf16 v[100:103], v[156:159], v[200:203], v[100:103]
	v_mfma_f32_16x16x32_bf16 v[96:99], v[184:187], v[200:203], v[96:99]
	v_mfma_f32_16x16x32_bf16 v[84:87], v[156:159], v[208:211], v[84:87]
	v_mfma_f32_16x16x32_bf16 v[80:83], v[184:187], v[208:211], v[80:83]
	v_mfma_f32_16x16x32_bf16 v[68:71], v[156:159], v[216:219], v[68:71]
	v_mfma_f32_16x16x32_bf16 v[64:67], v[184:187], v[216:219], v[64:67]
	s_setprio 0
	s_barrier
	s_add_u32 s6, s34, 0x80
	s_addc_u32 s7, s35, 0
	s_add_i32 s36, s59, s39
	s_mov_b32 m0, s36
	ds_read_b128 v[188:191], v177 offset:49152
	ds_read_b128 v[192:195], v177 offset:50176
	ds_read_b128 v[196:199], v177 offset:51200
	ds_read_b128 v[200:203], v177 offset:52224
	ds_read_b128 v[204:207], v177 offset:53248
	ds_read_b128 v[208:211], v177 offset:54272
	ds_read_b128 v[212:215], v177 offset:55296
	ds_read_b128 v[216:219], v177 offset:56320
	s_nop 0
	global_load_lds_dwordx4 v169, s[6:7]
	s_add_i32 m0, s36, 0x2000
	s_nop 0
	global_load_lds_dwordx4 v172, s[6:7]
	s_add_u32 s6, s34, 0x300080
	s_addc_u32 s7, s35, 0
	s_add_i32 s34, s60, s39
	s_mov_b32 m0, s34
	s_nop 0
	global_load_lds_dwordx4 v169, s[6:7]
	s_add_i32 m0, s34, 0x2000
	s_nop 0
	global_load_lds_dwordx4 v172, s[6:7]
	s_mov_b32 m0, s47
	s_nop 0
	global_load_lds_dwordx4 v167, s[30:31]
	s_mov_b32 m0, s48
	s_nop 0
	global_load_lds_dwordx4 v171, s[30:31]
	s_waitcnt vmcnt(8)
	s_waitcnt lgkmcnt(0)
	s_setprio 1
	s_waitcnt lgkmcnt(0)
	s_barrier
	v_mfma_f32_16x16x32_bf16 v[60:63], v[128:131], v[188:191], v[60:63]
	v_mfma_f32_16x16x32_bf16 v[56:59], v[136:139], v[188:191], v[56:59]
	v_mfma_f32_16x16x32_bf16 v[44:47], v[128:131], v[196:199], v[44:47]
	v_mfma_f32_16x16x32_bf16 v[40:43], v[136:139], v[196:199], v[40:43]
	v_mfma_f32_16x16x32_bf16 v[28:31], v[128:131], v[204:207], v[28:31]
	v_mfma_f32_16x16x32_bf16 v[24:27], v[136:139], v[204:207], v[24:27]
	v_mfma_f32_16x16x32_bf16 v[12:15], v[128:131], v[212:215], v[12:15]
	v_mfma_f32_16x16x32_bf16 v[8:11], v[136:139], v[212:215], v[8:11]
	v_mfma_f32_16x16x32_bf16 v[52:55], v[152:155], v[188:191], v[52:55]
	v_mfma_f32_16x16x32_bf16 v[48:51], v[160:163], v[188:191], v[48:51]
	v_mfma_f32_16x16x32_bf16 v[36:39], v[152:155], v[196:199], v[36:39]
	v_mfma_f32_16x16x32_bf16 v[32:35], v[160:163], v[196:199], v[32:35]
	v_mfma_f32_16x16x32_bf16 v[20:23], v[152:155], v[204:207], v[20:23]
	v_mfma_f32_16x16x32_bf16 v[16:19], v[160:163], v[204:207], v[16:19]
	v_mfma_f32_16x16x32_bf16 v[4:7], v[152:155], v[212:215], v[4:7]
	v_mfma_f32_16x16x32_bf16 v[0:3], v[160:163], v[212:215], v[0:3]
	v_mfma_f32_16x16x32_bf16 v[60:63], v[132:135], v[192:195], v[60:63]
	v_mfma_f32_16x16x32_bf16 v[56:59], v[140:143], v[192:195], v[56:59]
	v_mfma_f32_16x16x32_bf16 v[44:47], v[132:135], v[200:203], v[44:47]
	v_mfma_f32_16x16x32_bf16 v[40:43], v[140:143], v[200:203], v[40:43]
	v_mfma_f32_16x16x32_bf16 v[28:31], v[132:135], v[208:211], v[28:31]
	v_mfma_f32_16x16x32_bf16 v[24:27], v[140:143], v[208:211], v[24:27]
	v_mfma_f32_16x16x32_bf16 v[12:15], v[132:135], v[216:219], v[12:15]
	v_mfma_f32_16x16x32_bf16 v[8:11], v[140:143], v[216:219], v[8:11]
	v_mfma_f32_16x16x32_bf16 v[52:55], v[156:159], v[192:195], v[52:55]
	v_mfma_f32_16x16x32_bf16 v[48:51], v[184:187], v[192:195], v[48:51]
	v_mfma_f32_16x16x32_bf16 v[36:39], v[156:159], v[200:203], v[36:39]
	v_mfma_f32_16x16x32_bf16 v[32:35], v[184:187], v[200:203], v[32:35]
	v_mfma_f32_16x16x32_bf16 v[20:23], v[156:159], v[208:211], v[20:23]
	v_mfma_f32_16x16x32_bf16 v[16:19], v[184:187], v[208:211], v[16:19]
	v_mfma_f32_16x16x32_bf16 v[4:7], v[156:159], v[216:219], v[4:7]
	v_mfma_f32_16x16x32_bf16 v[0:3], v[184:187], v[216:219], v[0:3]
	s_setprio 0
	s_barrier
	s_add_i32 s58, s58, 2
	s_add_u32 s4, s4, 0x100
	s_addc_u32 s5, s5, 0
	s_cmpk_gt_u32 s58, 0xbd
	s_mov_b64 s[6:7], s[28:29]
	s_cbranch_scc0 .LBB0_1217
	s_and_b64 vcc, exec, s[18:19]
	s_cbranch_vccz .LBB0_1220
	s_barrier

; __global__ void __launch_bounds__(NWAVES * 64, 2) hyb_fwd(Args args) {
	.amdhsa_kernel _Z7hyb_fwd4Args
		.amdhsa_group_segment_fixed_size 0
		.amdhsa_private_segment_fixed_size 0
		.amdhsa_kernarg_size 464
		.amdhsa_user_sgpr_count 2
		.amdhsa_user_sgpr_dispatch_ptr 0
		.amdhsa_user_sgpr_queue_ptr 0
		.amdhsa_user_sgpr_kernarg_segment_ptr 1
		.amdhsa_user_sgpr_dispatch_id 0
		.amdhsa_user_sgpr_kernarg_preload_length 0
		.amdhsa_user_sgpr_kernarg_preload_offset 0
		.amdhsa_user_sgpr_private_segment_size 0
		.amdhsa_uses_dynamic_stack 0
		.amdhsa_enable_private_segment 0
		.amdhsa_system_sgpr_workgroup_id_x 1
		.amdhsa_system_sgpr_workgroup_id_y 0
		.amdhsa_system_sgpr_workgroup_id_z 0
		.amdhsa_system_sgpr_workgroup_info 0
		.amdhsa_system_vgpr_workitem_id 0
		.amdhsa_next_free_vgpr 256
		.amdhsa_next_free_sgpr 98
		.amdhsa_accum_offset 256
		.amdhsa_reserve_vcc 1
		.amdhsa_float_round_mode_32 0
		.amdhsa_float_round_mode_16_64 0
		.amdhsa_float_denorm_mode_32 3
		.amdhsa_float_denorm_mode_16_64 3
		.amdhsa_dx10_clamp 1
		.amdhsa_ieee_mode 1
		.amdhsa_fp16_overflow 0
		.amdhsa_tg_split 0
		.amdhsa_exception_fp_ieee_invalid_op 0
		.amdhsa_exception_fp_denorm_src 0
		.amdhsa_exception_fp_ieee_div_zero 0
		.amdhsa_exception_fp_ieee_overflow 0
		.amdhsa_exception_fp_ieee_underflow 0
		.amdhsa_exception_fp_ieee_inexact 0
		.amdhsa_exception_int_div_zero 0
	.end_amdhsa_kernel
